# K-loop: loop-invariant offset adds (4x offset+0x80, B-side LDS base) hoisted to the loop preheader: no VALU left in the load segments except none; M0 writes moved above last ds_read; previous edits
# speedup vs baseline: 1.0139x; 1.0079x over previous
; template <class Epi>
; __device__ __forceinline__ void gemm_phase(LAS unsigned char* lds, const Gemm g0, const StaticOrder& S, const Epi& E) {
;     ...
;         const bool has_next = S.next(ui + 1, nxt);
;         const char* nA = has_next ? (const char*)g.A + (size_t)nxt.pm * tstep : cA; const char* nB = has_next ? (const char*)g.Bt + (size_t)nxt.pn * tstep : cB;
;         for (int t = 0; t < nt; t += 2) {
;             const bool last = (t == nt - 2);
;             if (Epi::PREF && last) E.prefetch(cur, wr, wc, lane);
;             const char* a1 = cA + (size_t)(t + 1) * kstep;
;             const char* a2 = last ? nA : cA + (size_t)(t + 2) * kstep; const char* b2 = last ? nB : cB + (size_t)(t + 2) * kstep;
;             const char* a3 = a2 + kstep; const char* b3 = b2 + kstep;
;             PG8_LDB(B0, 0, 0); PG8_SCHED; PG8_LDA(At, 0, 0); PG8_STAGE(PG8_SA(1, 1), a1 + hstep, voffA);
;             PG8_WAIT_L(8); PG8_BAR; PG8_WAIT_L(0); PG8_MMA(0, 0, At, B0); PG8_BAR; PG8_SCHED;
;             PG8_LDB(B1, 0, 1); PG8_STAGE(PG8_SB(0, 0), b2, voffB);
;             PG8_BAR; PG8_WAIT_L(0); PG8_MMA(0, 1, At, B1); PG8_BAR;
;             PG8_LDA(At, 0, 1); PG8_STAGE(PG8_SA(0, 0), a2, voffA);
;             PG8_BAR; PG8_WAIT_L(0); PG8_MMA(1, 0, At, B0); PG8_BAR; PG8_SCHED;
;             PG8_STAGE(PG8_SB(0, 1), b2 + hstep, voffB);
;             PG8_WAIT_V(6); PG8_BAR; PG8_MMA(1, 1, At, B1); PG8_BAR;
;             PG8_LDB(B0, 1, 0); PG8_SCHED; PG8_LDA(At, 1, 0); PG8_STAGE(PG8_SA(0, 1), a2 + hstep, voffA);
;             PG8_WAIT_L(8); PG8_BAR; PG8_WAIT_L(0); PG8_MMA(0, 0, At, B0); PG8_BAR; PG8_SCHED;
;             PG8_LDB(B1, 1, 1); PG8_STAGE(PG8_SB(1, 0), b3, voffB);
;             PG8_BAR; PG8_WAIT_L(0); PG8_MMA(0, 1, At, B1); PG8_BAR;
;             PG8_LDA(At, 1, 1); PG8_STAGE(PG8_SA(1, 0), a3, voffA);
;             PG8_BAR; PG8_WAIT_L(0); PG8_MMA(1, 0, At, B0); PG8_BAR; PG8_SCHED;
;             PG8_STAGE(PG8_SB(1, 1), b3 + hstep, voffB);
;             PG8_WAIT_V(6); PG8_BAR; PG8_MMA(1, 1, At, B1); PG8_BAR;
;         }
;         if (Epi::PREF) asm volatile("s_waitcnt vmcnt(16)" ::: "memory");
;         E(acc, cur, wr, wc, fr, fq);
;         if (!has_next) break;
; #pragma unroll
;         for (int a = 0; a < 2; ++a)
; #pragma unroll
;             for (int b = 0; b < 2; ++b)
; #pragma unroll
;                 for (int m = 0; m < 4; ++m)
; #pragma unroll
.LBB0_197:
	s_ashr_i32 s37, s36, 31
	v_mov_b64_e32 v[2:3], 0x300
	s_lshl_b64 s[24:25], s[36:37], 20
	v_cmp_lt_i64_e32 vcc, s[38:39], v[2:3]
	s_add_u32 s38, s8, s24
	s_addc_u32 s39, s9, s25
	s_and_b64 s[24:25], vcc, exec
	s_cselect_b32 s75, s39, s51
	s_cselect_b32 s80, s38, s50
	s_ashr_i32 s35, s34, 31
	s_lshl_b64 s[24:25], s[34:35], 20
	s_add_u32 s48, s10, s24
	s_addc_u32 s49, s11, s25
	s_and_b64 s[24:25], vcc, exec
	s_cselect_b32 s81, s49, s1
	s_cselect_b32 s82, s48, s0
	s_lshl_b32 s37, s22, 8
	s_lshl_b32 s35, s74, 8
	v_add_u32_e32 v2, s37, v215
	v_add_u32_e32 v4, s35, v216
	s_add_u32 s24, s0, 0x100
	v_ashrrev_i32_e32 v3, 31, v2
	v_ashrrev_i32_e32 v5, 31, v4
	s_addc_u32 s25, s1, 0
	v_lshlrev_b64 v[4:5], 2, v[4:5]
	v_lshl_add_u64 v[134:135], v[2:3], 3, s[14:15]
	s_add_u32 s0, s50, 0x80080
	v_mov_b32_e32 v2, 0
	v_lshl_add_u64 v[130:131], s[26:27], 0, v[4:5]
	v_lshl_add_u64 v[132:133], s[20:21], 0, v[4:5]
	s_addc_u32 s1, s51, 0
	s_mov_b32 s83, -2
	v_mov_b32_e32 v3, v2
	v_mov_b32_e32 v4, v2
	v_mov_b32_e32 v5, v2
	v_mov_b32_e32 v6, v2
	v_mov_b32_e32 v7, v2
	v_mov_b32_e32 v8, v2
	v_mov_b32_e32 v9, v2
	v_mov_b32_e32 v10, v2
	v_mov_b32_e32 v11, v2
	v_mov_b32_e32 v12, v2
	v_mov_b32_e32 v13, v2
	v_mov_b32_e32 v14, v2
	v_mov_b32_e32 v15, v2
	v_mov_b32_e32 v16, v2
	v_mov_b32_e32 v17, v2
	v_mov_b32_e32 v26, v2
	v_mov_b32_e32 v27, v2
	v_mov_b32_e32 v28, v2
	v_mov_b32_e32 v29, v2
	v_mov_b32_e32 v34, v2
	v_mov_b32_e32 v35, v2
	v_mov_b32_e32 v36, v2
	v_mov_b32_e32 v37, v2
	v_mov_b32_e32 v42, v2
	v_mov_b32_e32 v43, v2
	v_mov_b32_e32 v44, v2
	v_mov_b32_e32 v45, v2
	v_mov_b32_e32 v46, v2
	v_mov_b32_e32 v47, v2
	v_mov_b32_e32 v48, v2
	v_mov_b32_e32 v49, v2
	v_mov_b32_e32 v18, v2
	v_mov_b32_e32 v19, v2
	v_mov_b32_e32 v20, v2
	v_mov_b32_e32 v21, v2
	v_mov_b32_e32 v22, v2
	v_mov_b32_e32 v23, v2
	v_mov_b32_e32 v24, v2
	v_mov_b32_e32 v25, v2
	v_mov_b32_e32 v30, v2
	v_mov_b32_e32 v31, v2
	v_mov_b32_e32 v32, v2
	v_mov_b32_e32 v33, v2
	v_mov_b32_e32 v38, v2
	v_mov_b32_e32 v39, v2
	v_mov_b32_e32 v40, v2
	v_mov_b32_e32 v41, v2
	v_mov_b32_e32 v50, v2
	v_mov_b32_e32 v51, v2
	v_mov_b32_e32 v52, v2
	v_mov_b32_e32 v53, v2
	v_mov_b32_e32 v54, v2
	v_mov_b32_e32 v55, v2
	v_mov_b32_e32 v56, v2
	v_mov_b32_e32 v57, v2
	v_mov_b32_e32 v58, v2
	v_mov_b32_e32 v59, v2
	v_mov_b32_e32 v60, v2
	v_mov_b32_e32 v61, v2
	v_mov_b32_e32 v62, v2
	v_mov_b32_e32 v63, v2
	v_mov_b32_e32 v64, v2
	v_mov_b32_e32 v65, v2
	v_mov_b32_e32 v66, v2
	v_mov_b32_e32 v67, v2
	v_mov_b32_e32 v68, v2
	v_mov_b32_e32 v69, v2
	v_mov_b32_e32 v70, v2
	v_mov_b32_e32 v71, v2
	v_mov_b32_e32 v72, v2
	v_mov_b32_e32 v73, v2
	v_mov_b32_e32 v74, v2
	v_mov_b32_e32 v75, v2
	v_mov_b32_e32 v76, v2
	v_mov_b32_e32 v77, v2
	v_mov_b32_e32 v78, v2
	v_mov_b32_e32 v79, v2
	v_mov_b32_e32 v80, v2
	v_mov_b32_e32 v81, v2
	v_mov_b32_e32 v90, v2
	v_mov_b32_e32 v91, v2
	v_mov_b32_e32 v92, v2
	v_mov_b32_e32 v93, v2
	v_mov_b32_e32 v94, v2
	v_mov_b32_e32 v95, v2
	v_mov_b32_e32 v96, v2
	v_mov_b32_e32 v97, v2
	v_mov_b32_e32 v106, v2
	v_mov_b32_e32 v107, v2
	v_mov_b32_e32 v108, v2
	v_mov_b32_e32 v109, v2
	v_mov_b32_e32 v114, v2
	v_mov_b32_e32 v115, v2
	v_mov_b32_e32 v116, v2
	v_mov_b32_e32 v117, v2
	v_mov_b32_e32 v82, v2
	v_mov_b32_e32 v83, v2
	v_mov_b32_e32 v84, v2
	v_mov_b32_e32 v85, v2
	v_mov_b32_e32 v86, v2
	v_mov_b32_e32 v87, v2
	v_mov_b32_e32 v88, v2
	v_mov_b32_e32 v89, v2
	v_mov_b32_e32 v98, v2
	v_mov_b32_e32 v99, v2
	v_mov_b32_e32 v100, v2
	v_mov_b32_e32 v101, v2
	v_mov_b32_e32 v102, v2
	v_mov_b32_e32 v103, v2
	v_mov_b32_e32 v104, v2
	v_mov_b32_e32 v105, v2
	v_mov_b32_e32 v110, v2
	v_mov_b32_e32 v111, v2
	v_mov_b32_e32 v112, v2
	v_mov_b32_e32 v113, v2
	v_mov_b32_e32 v118, v2
	v_mov_b32_e32 v119, v2
	v_mov_b32_e32 v120, v2
	v_mov_b32_e32 v121, v2
	v_mov_b32_e32 v122, v2
	v_mov_b32_e32 v123, v2
	v_mov_b32_e32 v124, v2
	v_mov_b32_e32 v125, v2
	v_mov_b32_e32 v126, v2
	v_mov_b32_e32 v127, v2
	v_mov_b32_e32 v128, v2
	v_mov_b32_e32 v129, v2
	v_add_u32_e32 v160, 0x80, v178
	v_add_u32_e32 v162, 0x80, v174
	v_add_u32_e32 v164, 0x80, v180
	v_add_u32_e32 v170, 0x80, v176
	v_add_u32_e32 v161, 0x10000, v214
	s_branch .LBB0_199
.LBB0_198:
	s_add_u32 s52, s0, 0xfff80080
	s_addc_u32 s53, s1, -1
	s_and_b64 s[22:23], s[50:51], exec
	s_cselect_b32 s53, s75, s53
	s_cselect_b32 s52, s80, s52
	s_add_i32 s84, 0, 0x10000
	ds_read_b128 v[136:139], v161
	ds_read_b128 v[140:143], v161 offset:1024
	ds_read_b128 v[144:147], v161 offset:2048
	ds_read_b128 v[148:151], v161 offset:3072
	s_and_b64 s[22:23], s[50:51], exec
	s_cselect_b32 s51, s81, s25
	s_cselect_b32 s50, s82, s24
	s_add_i32 m0, s28, 0xc000
	ds_read_b128 v[152:155], v222
	ds_read_b128 v[156:159], v222 offset:1024
	ds_read_b128 v[186:189], v222 offset:2048
	ds_read_b128 v[190:193], v222 offset:3072
	ds_read_b128 v[194:197], v222 offset:4096
	ds_read_b128 v[198:201], v222 offset:5120
	ds_read_b128 v[202:205], v222 offset:6144
	ds_read_b128 v[206:209], v222 offset:7168
	global_load_lds_dwordx4 v184, s[0:1]
	s_add_i32 m0, s28, 0xe000
	s_nop 0
	global_load_lds_dwordx4 v182, s[0:1]
	s_waitcnt lgkmcnt(8)
	s_barrier
	s_waitcnt lgkmcnt(0)
	s_waitcnt lgkmcnt(0)
	v_mfma_f32_16x16x32_f16 v[126:129], v[136:139], v[152:155], v[126:129]
	v_mfma_f32_16x16x32_f16 v[122:125], v[144:147], v[152:155], v[122:125]
	v_mfma_f32_16x16x32_f16 v[118:121], v[136:139], v[186:189], v[118:121]
	v_mfma_f32_16x16x32_f16 v[110:113], v[144:147], v[186:189], v[110:113]
	v_mfma_f32_16x16x32_f16 v[102:105], v[136:139], v[194:197], v[102:105]
	v_mfma_f32_16x16x32_f16 v[98:101], v[144:147], v[194:197], v[98:101]
	v_mfma_f32_16x16x32_f16 v[86:89], v[136:139], v[202:205], v[86:89]
	v_mfma_f32_16x16x32_f16 v[82:85], v[144:147], v[202:205], v[82:85]
	v_mfma_f32_16x16x32_f16 v[126:129], v[140:143], v[156:159], v[126:129]
	v_mfma_f32_16x16x32_f16 v[122:125], v[148:151], v[156:159], v[122:125]
	v_mfma_f32_16x16x32_f16 v[118:121], v[140:143], v[190:193], v[118:121]
	v_mfma_f32_16x16x32_f16 v[110:113], v[148:151], v[190:193], v[110:113]
	v_mfma_f32_16x16x32_f16 v[102:105], v[140:143], v[198:201], v[102:105]
	v_mfma_f32_16x16x32_f16 v[98:101], v[148:151], v[198:201], v[98:101]
	v_mfma_f32_16x16x32_f16 v[86:89], v[140:143], v[206:209], v[86:89]
	v_mfma_f32_16x16x32_f16 v[82:85], v[148:151], v[206:209], v[82:85]
	s_barrier
; #define PG8_STAGE(bufoff, gbase, voff) do { _Pragma("unroll") for (int _i = 0; _i < 2; ++_i) \
;         __builtin_amdgcn_global_load_lds((const unsigned*)((const char*)(gbase) + (voff)[_i]), (LAS unsigned*)(lds + (bufoff) + ldsw + _i * 8192), 16, 0, 0); } while (0)
; #define PG8_LDA(dst, b, h) do { _Pragma("unroll") for (int m = 0; m < 4; ++m) _Pragma("unroll") for (int k = 0; k < 2; ++k) dst[m][k] = *(const LAS f16x8*)(lds + PG8_SA(b, h) + aoff + m * 2048 + k * 1024); } while (0)
; #define PG8_LDB(dst, b, h) do { _Pragma("unroll") for (int n = 0; n < 2; ++n) _Pragma("unroll") for (int k = 0; k < 2; ++k) dst[n][k] = *(const LAS f16x8*)(lds + PG8_SB(b, h) + boff + n * 2048 + k * 1024); } while (0)
; #define PG8_MMA(ai, bj, At, Bt) do { __builtin_amdgcn_s_setprio(1); _Pragma("unroll") for (int m = 0; m < 4; ++m) _Pragma("unroll") for (int n = 0; n < 2; ++n) _Pragma("unroll") for (int k = 0; k < 2; ++k) \
;         acc[ai][bj][m][n] = __builtin_amdgcn_mfma_f32_16x16x32_f16(Bt[n][k], At[m][k], acc[ai][bj][m][n], 0, 0, 0); __builtin_amdgcn_s_setprio(0); } while (0)
; #define PG8_WAIT_V(n) asm volatile("s_waitcnt vmcnt(" #n ")" ::: "memory")
; #define PG8_WAIT_L(n) asm volatile("s_waitcnt lgkmcnt(" #n ")" ::: "memory")
; #define PG8_BAR __builtin_amdgcn_s_barrier()
; #define PG8_SCHED __builtin_amdgcn_sched_barrier(0)
; template <class Epi>
; __device__ __forceinline__ void gemm_phase(LAS unsigned char* lds, const Gemm g0, const StaticOrder& S, const Epi& E) {
;     ...
;             PG8_LDB(B1, 0, 1); PG8_STAGE(PG8_SB(0, 0), b2, voffB);
;             PG8_BAR; PG8_WAIT_L(0); PG8_MMA(0, 1, At, B1); PG8_BAR;
;             PG8_LDA(At, 0, 1); PG8_STAGE(PG8_SA(0, 0), a2, voffA);
;             PG8_BAR; PG8_WAIT_L(0); PG8_MMA(1, 0, At, B0); PG8_BAR; PG8_SCHED;
;             PG8_STAGE(PG8_SB(0, 1), b2 + hstep, voffB);
;             PG8_WAIT_V(6); PG8_BAR; PG8_MMA(1, 1, At, B1); PG8_BAR;
;             PG8_LDB(B0, 1, 0); PG8_SCHED; PG8_LDA(At, 1, 0); PG8_STAGE(PG8_SA(0, 1), a2 + hstep, voffA);
;             PG8_WAIT_L(8); PG8_BAR; PG8_WAIT_L(0); PG8_MMA(0, 0, At, B0); PG8_BAR; PG8_SCHED;
	s_add_i32 s85, 0, 0x14000
	s_add_i32 s22, s84, s19
	ds_read_b128 v[210:213], v161 offset:16384
	ds_read_b128 v[234:237], v161 offset:17408
	ds_read_b128 v[238:241], v161 offset:18432
	s_mov_b32 m0, s22
	ds_read_b128 v[242:245], v161 offset:19456
	global_load_lds_dwordx4 v178, s[50:51]
	s_add_i32 m0, s22, 0x2000
	s_nop 0
	global_load_lds_dwordx4 v174, s[50:51]
	s_barrier
	s_waitcnt lgkmcnt(0)
	s_waitcnt lgkmcnt(0)
	v_mfma_f32_16x16x32_f16 v[114:117], v[210:213], v[152:155], v[114:117]
	v_mfma_f32_16x16x32_f16 v[106:109], v[238:241], v[152:155], v[106:109]
	v_mfma_f32_16x16x32_f16 v[94:97], v[210:213], v[186:189], v[94:97]
	v_mfma_f32_16x16x32_f16 v[90:93], v[238:241], v[186:189], v[90:93]
	v_mfma_f32_16x16x32_f16 v[78:81], v[210:213], v[194:197], v[78:81]
	v_mfma_f32_16x16x32_f16 v[74:77], v[238:241], v[194:197], v[74:77]
	v_mfma_f32_16x16x32_f16 v[70:73], v[210:213], v[202:205], v[70:73]
	v_mfma_f32_16x16x32_f16 v[66:69], v[238:241], v[202:205], v[66:69]
	v_mfma_f32_16x16x32_f16 v[114:117], v[234:237], v[156:159], v[114:117]
	v_mfma_f32_16x16x32_f16 v[106:109], v[242:245], v[156:159], v[106:109]
	v_mfma_f32_16x16x32_f16 v[94:97], v[234:237], v[190:193], v[94:97]
	v_mfma_f32_16x16x32_f16 v[90:93], v[242:245], v[190:193], v[90:93]
	v_mfma_f32_16x16x32_f16 v[78:81], v[234:237], v[198:201], v[78:81]
	v_mfma_f32_16x16x32_f16 v[74:77], v[242:245], v[198:201], v[74:77]
	v_mfma_f32_16x16x32_f16 v[70:73], v[234:237], v[206:209], v[70:73]
	v_mfma_f32_16x16x32_f16 v[66:69], v[242:245], v[206:209], v[66:69]
	s_mov_b32 m0, s28
	s_barrier
	ds_read_b128 v[152:155], v222 offset:16384
	ds_read_b128 v[156:159], v222 offset:17408
	ds_read_b128 v[186:189], v222 offset:18432
	ds_read_b128 v[190:193], v222 offset:19456
	ds_read_b128 v[194:197], v222 offset:20480
	ds_read_b128 v[198:201], v222 offset:21504
	ds_read_b128 v[202:205], v222 offset:22528
	ds_read_b128 v[206:209], v222 offset:23552
	global_load_lds_dwordx4 v180, s[52:53]
	s_mov_b32 m0, s29
	s_nop 0
	global_load_lds_dwordx4 v176, s[52:53]
	s_barrier
	s_waitcnt lgkmcnt(0)
	s_waitcnt lgkmcnt(0)
	v_mfma_f32_16x16x32_f16 v[62:65], v[136:139], v[152:155], v[62:65]
	v_mfma_f32_16x16x32_f16 v[58:61], v[144:147], v[152:155], v[58:61]
	v_mfma_f32_16x16x32_f16 v[54:57], v[136:139], v[186:189], v[54:57]
	v_mfma_f32_16x16x32_f16 v[50:53], v[144:147], v[186:189], v[50:53]
	v_mfma_f32_16x16x32_f16 v[38:41], v[136:139], v[194:197], v[38:41]
	v_mfma_f32_16x16x32_f16 v[30:33], v[144:147], v[194:197], v[30:33]
	v_mfma_f32_16x16x32_f16 v[22:25], v[136:139], v[202:205], v[22:25]
	v_mfma_f32_16x16x32_f16 v[18:21], v[144:147], v[202:205], v[18:21]
	v_mfma_f32_16x16x32_f16 v[62:65], v[140:143], v[156:159], v[62:65]
	v_mfma_f32_16x16x32_f16 v[58:61], v[148:151], v[156:159], v[58:61]
	v_mfma_f32_16x16x32_f16 v[54:57], v[140:143], v[190:193], v[54:57]
	v_mfma_f32_16x16x32_f16 v[50:53], v[148:151], v[190:193], v[50:53]
	v_mfma_f32_16x16x32_f16 v[38:41], v[140:143], v[198:201], v[38:41]
	v_mfma_f32_16x16x32_f16 v[30:33], v[148:151], v[198:201], v[30:33]
	v_mfma_f32_16x16x32_f16 v[22:25], v[140:143], v[206:209], v[22:25]
	v_mfma_f32_16x16x32_f16 v[18:21], v[148:151], v[206:209], v[18:21]
	s_barrier
	s_add_u32 s22, s50, 0x80000
	s_addc_u32 s23, s51, 0
	s_add_i32 s84, s85, s19
	s_mov_b32 m0, s84
	s_nop 0
	global_load_lds_dwordx4 v178, s[22:23]
	s_add_i32 m0, s84, 0x2000
	s_nop 0
	global_load_lds_dwordx4 v174, s[22:23]
	s_waitcnt vmcnt(6)
	s_barrier
	v_mfma_f32_16x16x32_f16 v[46:49], v[210:213], v[152:155], v[46:49]
	v_mfma_f32_16x16x32_f16 v[42:45], v[238:241], v[152:155], v[42:45]
	v_mfma_f32_16x16x32_f16 v[34:37], v[210:213], v[186:189], v[34:37]
	v_mfma_f32_16x16x32_f16 v[26:29], v[238:241], v[186:189], v[26:29]
	v_mfma_f32_16x16x32_f16 v[14:17], v[210:213], v[194:197], v[14:17]
	v_mfma_f32_16x16x32_f16 v[10:13], v[238:241], v[194:197], v[10:13]
	v_mfma_f32_16x16x32_f16 v[6:9], v[210:213], v[202:205], v[6:9]
	v_mfma_f32_16x16x32_f16 v[2:5], v[238:241], v[202:205], v[2:5]
	v_mfma_f32_16x16x32_f16 v[46:49], v[234:237], v[156:159], v[46:49]
	v_mfma_f32_16x16x32_f16 v[42:45], v[242:245], v[156:159], v[42:45]
	v_mfma_f32_16x16x32_f16 v[34:37], v[234:237], v[190:193], v[34:37]
	v_mfma_f32_16x16x32_f16 v[26:29], v[242:245], v[190:193], v[26:29]
	v_mfma_f32_16x16x32_f16 v[14:17], v[234:237], v[198:201], v[14:17]
	v_mfma_f32_16x16x32_f16 v[10:13], v[242:245], v[198:201], v[10:13]
	v_mfma_f32_16x16x32_f16 v[6:9], v[234:237], v[206:209], v[6:9]
	v_mfma_f32_16x16x32_f16 v[2:5], v[242:245], v[206:209], v[2:5]
	s_add_i32 s84, 0, 0x18000
	s_barrier
	ds_read_b128 v[136:139], v161 offset:32768
	ds_read_b128 v[140:143], v161 offset:33792
	ds_read_b128 v[144:147], v161 offset:34816
	ds_read_b128 v[148:151], v161 offset:35840
	s_add_u32 s22, s52, 0x80000
	s_addc_u32 s23, s53, 0
	s_mov_b32 m0, s31
	ds_read_b128 v[152:155], v222 offset:32768
	ds_read_b128 v[156:159], v222 offset:33792
	ds_read_b128 v[186:189], v222 offset:34816
	ds_read_b128 v[190:193], v222 offset:35840
	ds_read_b128 v[194:197], v222 offset:36864
	ds_read_b128 v[198:201], v222 offset:37888
	ds_read_b128 v[202:205], v222 offset:38912
	ds_read_b128 v[206:209], v222 offset:39936
	global_load_lds_dwordx4 v180, s[22:23]
	s_mov_b32 m0, s58
	s_nop 0
	global_load_lds_dwordx4 v176, s[22:23]
	s_waitcnt lgkmcnt(8)
	s_barrier
; #define PG8_STAGE(bufoff, gbase, voff) do { _Pragma("unroll") for (int _i = 0; _i < 2; ++_i) \
;         __builtin_amdgcn_global_load_lds((const unsigned*)((const char*)(gbase) + (voff)[_i]), (LAS unsigned*)(lds + (bufoff) + ldsw + _i * 8192), 16, 0, 0); } while (0)
; #define PG8_LDA(dst, b, h) do { _Pragma("unroll") for (int m = 0; m < 4; ++m) _Pragma("unroll") for (int k = 0; k < 2; ++k) dst[m][k] = *(const LAS f16x8*)(lds + PG8_SA(b, h) + aoff + m * 2048 + k * 1024); } while (0)
; #define PG8_LDB(dst, b, h) do { _Pragma("unroll") for (int n = 0; n < 2; ++n) _Pragma("unroll") for (int k = 0; k < 2; ++k) dst[n][k] = *(const LAS f16x8*)(lds + PG8_SB(b, h) + boff + n * 2048 + k * 1024); } while (0)
; #define PG8_MMA(ai, bj, At, Bt) do { __builtin_amdgcn_s_setprio(1); _Pragma("unroll") for (int m = 0; m < 4; ++m) _Pragma("unroll") for (int n = 0; n < 2; ++n) _Pragma("unroll") for (int k = 0; k < 2; ++k) \
;         acc[ai][bj][m][n] = __builtin_amdgcn_mfma_f32_16x16x32_f16(Bt[n][k], At[m][k], acc[ai][bj][m][n], 0, 0, 0); __builtin_amdgcn_s_setprio(0); } while (0)
; #define PG8_WAIT_V(n) asm volatile("s_waitcnt vmcnt(" #n ")" ::: "memory")
; #define PG8_WAIT_L(n) asm volatile("s_waitcnt lgkmcnt(" #n ")" ::: "memory")
; #define PG8_BAR __builtin_amdgcn_s_barrier()
; #define PG8_SCHED __builtin_amdgcn_sched_barrier(0)
; template <class Epi>
; __device__ __forceinline__ void gemm_phase(LAS unsigned char* lds, const Gemm g0, const StaticOrder& S, const Epi& E) {
;     ...
;             PG8_WAIT_L(8); PG8_BAR; PG8_WAIT_L(0); PG8_MMA(0, 0, At, B0); PG8_BAR; PG8_SCHED;
;             PG8_LDB(B1, 1, 1); PG8_STAGE(PG8_SB(1, 0), b3, voffB);
;             PG8_BAR; PG8_WAIT_L(0); PG8_MMA(0, 1, At, B1); PG8_BAR;
;             PG8_LDA(At, 1, 1); PG8_STAGE(PG8_SA(1, 0), a3, voffA);
;             PG8_BAR; PG8_WAIT_L(0); PG8_MMA(1, 0, At, B0); PG8_BAR; PG8_SCHED;
;             PG8_STAGE(PG8_SB(1, 1), b3 + hstep, voffB);
;             PG8_WAIT_V(6); PG8_BAR; PG8_MMA(1, 1, At, B1); PG8_BAR;
;         }
	s_waitcnt lgkmcnt(0)
	s_waitcnt lgkmcnt(0)
	v_mfma_f32_16x16x32_f16 v[126:129], v[136:139], v[152:155], v[126:129]
	v_mfma_f32_16x16x32_f16 v[122:125], v[144:147], v[152:155], v[122:125]
	v_mfma_f32_16x16x32_f16 v[118:121], v[136:139], v[186:189], v[118:121]
	v_mfma_f32_16x16x32_f16 v[110:113], v[144:147], v[186:189], v[110:113]
	v_mfma_f32_16x16x32_f16 v[102:105], v[136:139], v[194:197], v[102:105]
	v_mfma_f32_16x16x32_f16 v[98:101], v[144:147], v[194:197], v[98:101]
	v_mfma_f32_16x16x32_f16 v[86:89], v[136:139], v[202:205], v[86:89]
	v_mfma_f32_16x16x32_f16 v[82:85], v[144:147], v[202:205], v[82:85]
	v_mfma_f32_16x16x32_f16 v[126:129], v[140:143], v[156:159], v[126:129]
	v_mfma_f32_16x16x32_f16 v[122:125], v[148:151], v[156:159], v[122:125]
	v_mfma_f32_16x16x32_f16 v[118:121], v[140:143], v[190:193], v[118:121]
	v_mfma_f32_16x16x32_f16 v[110:113], v[148:151], v[190:193], v[110:113]
	v_mfma_f32_16x16x32_f16 v[102:105], v[140:143], v[198:201], v[102:105]
	v_mfma_f32_16x16x32_f16 v[98:101], v[148:151], v[198:201], v[98:101]
	v_mfma_f32_16x16x32_f16 v[86:89], v[140:143], v[206:209], v[86:89]
	v_mfma_f32_16x16x32_f16 v[82:85], v[148:151], v[206:209], v[82:85]
	s_barrier
	s_add_i32 s85, 0, 0x1c000
	s_add_i32 s22, s84, s19
	s_mov_b32 m0, s22
	ds_read_b128 v[210:213], v161 offset:49152
	ds_read_b128 v[234:237], v161 offset:50176
	ds_read_b128 v[238:241], v161 offset:51200
	ds_read_b128 v[242:245], v161 offset:52224
	global_load_lds_dwordx4 v160, s[50:51]
	s_add_i32 m0, s22, 0x2000
	s_nop 0
	global_load_lds_dwordx4 v162, s[50:51]
	s_barrier
	s_waitcnt lgkmcnt(0)
	s_waitcnt lgkmcnt(0)
	v_mfma_f32_16x16x32_f16 v[114:117], v[210:213], v[152:155], v[114:117]
	v_mfma_f32_16x16x32_f16 v[106:109], v[238:241], v[152:155], v[106:109]
	v_mfma_f32_16x16x32_f16 v[94:97], v[210:213], v[186:189], v[94:97]
	v_mfma_f32_16x16x32_f16 v[90:93], v[238:241], v[186:189], v[90:93]
	v_mfma_f32_16x16x32_f16 v[78:81], v[210:213], v[194:197], v[78:81]
	v_mfma_f32_16x16x32_f16 v[74:77], v[238:241], v[194:197], v[74:77]
	v_mfma_f32_16x16x32_f16 v[70:73], v[210:213], v[202:205], v[70:73]
	v_mfma_f32_16x16x32_f16 v[66:69], v[238:241], v[202:205], v[66:69]
	v_mfma_f32_16x16x32_f16 v[114:117], v[234:237], v[156:159], v[114:117]
	v_mfma_f32_16x16x32_f16 v[106:109], v[242:245], v[156:159], v[106:109]
	v_mfma_f32_16x16x32_f16 v[94:97], v[234:237], v[190:193], v[94:97]
	v_mfma_f32_16x16x32_f16 v[90:93], v[242:245], v[190:193], v[90:93]
	v_mfma_f32_16x16x32_f16 v[78:81], v[234:237], v[198:201], v[78:81]
	v_mfma_f32_16x16x32_f16 v[74:77], v[242:245], v[198:201], v[74:77]
	v_mfma_f32_16x16x32_f16 v[70:73], v[234:237], v[206:209], v[70:73]
	v_mfma_f32_16x16x32_f16 v[66:69], v[242:245], v[206:209], v[66:69]
	s_mov_b32 m0, s59
	s_barrier
	ds_read_b128 v[152:155], v222 offset:49152
	ds_read_b128 v[156:159], v222 offset:50176
	ds_read_b128 v[186:189], v222 offset:51200
	ds_read_b128 v[190:193], v222 offset:52224
	ds_read_b128 v[194:197], v222 offset:53248
	ds_read_b128 v[198:201], v222 offset:54272
	ds_read_b128 v[202:205], v222 offset:55296
	ds_read_b128 v[206:209], v222 offset:56320
	global_load_lds_dwordx4 v164, s[52:53]
	s_mov_b32 m0, s61
	s_nop 0
	global_load_lds_dwordx4 v170, s[52:53]
	s_barrier
	s_waitcnt lgkmcnt(0)
	s_waitcnt lgkmcnt(0)
	v_mfma_f32_16x16x32_f16 v[62:65], v[136:139], v[152:155], v[62:65]
	v_mfma_f32_16x16x32_f16 v[58:61], v[144:147], v[152:155], v[58:61]
	v_mfma_f32_16x16x32_f16 v[54:57], v[136:139], v[186:189], v[54:57]
	v_mfma_f32_16x16x32_f16 v[50:53], v[144:147], v[186:189], v[50:53]
	v_mfma_f32_16x16x32_f16 v[38:41], v[136:139], v[194:197], v[38:41]
	v_mfma_f32_16x16x32_f16 v[30:33], v[144:147], v[194:197], v[30:33]
	v_mfma_f32_16x16x32_f16 v[22:25], v[136:139], v[202:205], v[22:25]
	v_mfma_f32_16x16x32_f16 v[18:21], v[144:147], v[202:205], v[18:21]
	v_mfma_f32_16x16x32_f16 v[62:65], v[140:143], v[156:159], v[62:65]
	v_mfma_f32_16x16x32_f16 v[58:61], v[148:151], v[156:159], v[58:61]
	v_mfma_f32_16x16x32_f16 v[54:57], v[140:143], v[190:193], v[54:57]
	v_mfma_f32_16x16x32_f16 v[50:53], v[148:151], v[190:193], v[50:53]
	v_mfma_f32_16x16x32_f16 v[38:41], v[140:143], v[198:201], v[38:41]
	v_mfma_f32_16x16x32_f16 v[30:33], v[148:151], v[198:201], v[30:33]
	v_mfma_f32_16x16x32_f16 v[22:25], v[140:143], v[206:209], v[22:25]
	v_mfma_f32_16x16x32_f16 v[18:21], v[148:151], v[206:209], v[18:21]
	s_barrier
	s_add_u32 s22, s50, 0x80080
	s_addc_u32 s23, s51, 0
	s_add_i32 s50, s85, s19
	s_mov_b32 m0, s50
	s_nop 0
	global_load_lds_dwordx4 v178, s[22:23]
	s_add_i32 m0, s50, 0x2000
	s_nop 0
	global_load_lds_dwordx4 v174, s[22:23]
	s_waitcnt vmcnt(6)
	s_barrier
	v_mfma_f32_16x16x32_f16 v[46:49], v[210:213], v[152:155], v[46:49]
	v_mfma_f32_16x16x32_f16 v[42:45], v[238:241], v[152:155], v[42:45]
	v_mfma_f32_16x16x32_f16 v[34:37], v[210:213], v[186:189], v[34:37]
	v_mfma_f32_16x16x32_f16 v[26:29], v[238:241], v[186:189], v[26:29]
	v_mfma_f32_16x16x32_f16 v[14:17], v[210:213], v[194:197], v[14:17]
	v_mfma_f32_16x16x32_f16 v[10:13], v[238:241], v[194:197], v[10:13]
	v_mfma_f32_16x16x32_f16 v[6:9], v[210:213], v[202:205], v[6:9]
	v_mfma_f32_16x16x32_f16 v[2:5], v[238:241], v[202:205], v[2:5]
	v_mfma_f32_16x16x32_f16 v[46:49], v[234:237], v[156:159], v[46:49]
	v_mfma_f32_16x16x32_f16 v[42:45], v[242:245], v[156:159], v[42:45]
	v_mfma_f32_16x16x32_f16 v[34:37], v[234:237], v[190:193], v[34:37]
	v_mfma_f32_16x16x32_f16 v[26:29], v[242:245], v[190:193], v[26:29]
	v_mfma_f32_16x16x32_f16 v[14:17], v[234:237], v[198:201], v[14:17]
	v_mfma_f32_16x16x32_f16 v[10:13], v[242:245], v[198:201], v[10:13]
	v_mfma_f32_16x16x32_f16 v[6:9], v[234:237], v[206:209], v[6:9]
	v_mfma_f32_16x16x32_f16 v[2:5], v[242:245], v[206:209], v[2:5]
	s_add_i32 s83, s83, 2
	s_add_u32 s24, s24, 0x100
	s_addc_u32 s25, s25, 0
	s_add_u32 s0, s0, 0x100
	s_addc_u32 s1, s1, 0
	s_cmp_gt_u32 s83, 29
	s_barrier
	s_cbranch_scc1 .LBB0_201

;     __device__ __forceinline__ void prefetch(const Unit& u, int wr, int wc, int lane) const { lnfold_prefetch(vl, stats, gW, bW, u, wr, wc, lane); }
;     __device__ __forceinline__ void prefetch(const Unit& u, int wr, int wc, int lane) const { lnfold_prefetch(vl, stats, gW, bW, u, wr, wc, lane); }
; #define PG8_STAGE(bufoff, gbase, voff) do { _Pragma("unroll") for (int _i = 0; _i < 2; ++_i) \
;         __builtin_amdgcn_global_load_lds((const unsigned*)((const char*)(gbase) + (voff)[_i]), (LAS unsigned*)(lds + (bufoff) + ldsw + _i * 8192), 16, 0, 0); } while (0)
; #define PG8_LDA(dst, b, h) do { _Pragma("unroll") for (int m = 0; m < 4; ++m) _Pragma("unroll") for (int k = 0; k < 2; ++k) dst[m][k] = *(const LAS f16x8*)(lds + PG8_SA(b, h) + aoff + m * 2048 + k * 1024); } while (0)
; #define PG8_LDB(dst, b, h) do { _Pragma("unroll") for (int n = 0; n < 2; ++n) _Pragma("unroll") for (int k = 0; k < 2; ++k) dst[n][k] = *(const LAS f16x8*)(lds + PG8_SB(b, h) + boff + n * 2048 + k * 1024); } while (0)
; #define PG8_BAR __builtin_amdgcn_s_barrier()
; template <class Epi>
; __device__ __forceinline__ void gemm_phase(LAS unsigned char* lds, const Gemm g0, const StaticOrder& S, const Epi& E) {
;     ...
;         const bool has_next = S.next(ui + 1, nxt);
;         const char* nA = has_next ? (const char*)g.A + (size_t)nxt.pm * tstep : cA; const char* nB = has_next ? (const char*)g.Bt + (size_t)nxt.pn * tstep : cB;
;         for (int t = 0; t < nt; t += 2) {
;             const bool last = (t == nt - 2);
;             if (Epi::PREF && last) E.prefetch(cur, wr, wc, lane);
;             const char* a1 = cA + (size_t)(t + 1) * kstep;
;             const char* a2 = last ? nA : cA + (size_t)(t + 2) * kstep; const char* b2 = last ? nB : cB + (size_t)(t + 2) * kstep;
;             const char* a3 = a2 + kstep; const char* b3 = b2 + kstep;
;             PG8_LDB(B0, 0, 0); PG8_SCHED; PG8_LDA(At, 0, 0); PG8_STAGE(PG8_SA(1, 1), a1 + hstep, voffA);
;             PG8_WAIT_L(8); PG8_BAR; PG8_WAIT_L(0); PG8_MMA(0, 0, At, B0); PG8_BAR; PG8_SCHED;
;     ...
; #pragma unroll
;         for (int a = 0; a < 2; ++a)
; #pragma unroll
;             for (int b = 0; b < 2; ++b)
; #pragma unroll
;                 for (int m = 0; m < 4; ++m)
; #pragma unroll
;                     for (int n = 0; n < 2; ++n) acc[a][b][m][n] = (f32x4){0.f, 0.f, 0.f, 0.f};
;         cur = nxt; cA = nA; cB = nB; ++ui;
.LBB0_301:
	s_ashr_i32 s15, s14, 31
	v_cmp_lt_i64_e32 vcc, s[20:21], v[248:249]
	s_lshl_b64 s[20:21], s[14:15], 20
	s_add_u32 s20, s8, s20
	s_addc_u32 s21, s9, s21
	s_and_b64 s[22:23], vcc, exec
	s_cselect_b32 s15, s21, s35
	s_cselect_b32 s52, s20, s34
	s_ashr_i32 s13, s12, 31
	s_lshl_b64 s[22:23], s[12:13], 20
	s_add_u32 s26, s10, s22
	s_addc_u32 s27, s11, s23
	s_and_b64 s[22:23], vcc, exec
	s_cselect_b32 s13, s27, s7
	s_cselect_b32 s24, s26, s6
	s_add_u32 s25, s6, 0x100
	s_addc_u32 s53, s7, 0
	s_add_u32 s6, s34, 0x80080
	v_mov_b32_e32 v2, 0
	s_addc_u32 s7, s35, 0
	s_mov_b32 s58, -2
	v_mov_b32_e32 v3, v2
	v_mov_b32_e32 v4, v2
	v_mov_b32_e32 v5, v2
	v_mov_b32_e32 v6, v2
	v_mov_b32_e32 v7, v2
	v_mov_b32_e32 v8, v2
	v_mov_b32_e32 v9, v2
	v_mov_b32_e32 v18, v2
	v_mov_b32_e32 v19, v2
	v_mov_b32_e32 v20, v2
	v_mov_b32_e32 v21, v2
	v_mov_b32_e32 v22, v2
	v_mov_b32_e32 v23, v2
	v_mov_b32_e32 v24, v2
	v_mov_b32_e32 v25, v2
	v_mov_b32_e32 v34, v2
	v_mov_b32_e32 v35, v2
	v_mov_b32_e32 v36, v2
	v_mov_b32_e32 v37, v2
	v_mov_b32_e32 v38, v2
	v_mov_b32_e32 v39, v2
	v_mov_b32_e32 v40, v2
	v_mov_b32_e32 v41, v2
	v_mov_b32_e32 v50, v2
	v_mov_b32_e32 v51, v2
	v_mov_b32_e32 v52, v2
	v_mov_b32_e32 v53, v2
	v_mov_b32_e32 v54, v2
	v_mov_b32_e32 v55, v2
	v_mov_b32_e32 v56, v2
	v_mov_b32_e32 v57, v2
	v_mov_b32_e32 v10, v2
	v_mov_b32_e32 v11, v2
	v_mov_b32_e32 v12, v2
	v_mov_b32_e32 v13, v2
	v_mov_b32_e32 v14, v2
	v_mov_b32_e32 v15, v2
	v_mov_b32_e32 v16, v2
	v_mov_b32_e32 v17, v2
	v_mov_b32_e32 v26, v2
	v_mov_b32_e32 v27, v2
	v_mov_b32_e32 v28, v2
	v_mov_b32_e32 v29, v2
	v_mov_b32_e32 v30, v2
	v_mov_b32_e32 v31, v2
	v_mov_b32_e32 v32, v2
	v_mov_b32_e32 v33, v2
	v_mov_b32_e32 v42, v2
	v_mov_b32_e32 v43, v2
	v_mov_b32_e32 v44, v2
	v_mov_b32_e32 v45, v2
	v_mov_b32_e32 v46, v2
	v_mov_b32_e32 v47, v2
	v_mov_b32_e32 v48, v2
	v_mov_b32_e32 v49, v2
	v_mov_b32_e32 v58, v2
	v_mov_b32_e32 v59, v2
	v_mov_b32_e32 v60, v2
	v_mov_b32_e32 v61, v2
	v_mov_b32_e32 v62, v2
	v_mov_b32_e32 v63, v2
	v_mov_b32_e32 v64, v2
	v_mov_b32_e32 v65, v2
	v_mov_b32_e32 v66, v2
	v_mov_b32_e32 v67, v2
	v_mov_b32_e32 v68, v2
	v_mov_b32_e32 v69, v2
	v_mov_b32_e32 v70, v2
	v_mov_b32_e32 v71, v2
	v_mov_b32_e32 v72, v2
	v_mov_b32_e32 v73, v2
	v_mov_b32_e32 v82, v2
	v_mov_b32_e32 v83, v2
	v_mov_b32_e32 v84, v2
	v_mov_b32_e32 v85, v2
	v_mov_b32_e32 v86, v2
	v_mov_b32_e32 v87, v2
	v_mov_b32_e32 v88, v2
	v_mov_b32_e32 v89, v2
	v_mov_b32_e32 v98, v2
	v_mov_b32_e32 v99, v2
	v_mov_b32_e32 v100, v2
	v_mov_b32_e32 v101, v2
	v_mov_b32_e32 v102, v2
	v_mov_b32_e32 v103, v2
	v_mov_b32_e32 v104, v2
	v_mov_b32_e32 v105, v2
	v_mov_b32_e32 v114, v2
	v_mov_b32_e32 v115, v2
	v_mov_b32_e32 v116, v2
	v_mov_b32_e32 v117, v2
	v_mov_b32_e32 v118, v2
	v_mov_b32_e32 v119, v2
	v_mov_b32_e32 v120, v2
	v_mov_b32_e32 v121, v2
	v_mov_b32_e32 v74, v2
	v_mov_b32_e32 v75, v2
	v_mov_b32_e32 v76, v2
	v_mov_b32_e32 v77, v2
	v_mov_b32_e32 v78, v2
	v_mov_b32_e32 v79, v2
	v_mov_b32_e32 v80, v2
	v_mov_b32_e32 v81, v2
	v_mov_b32_e32 v90, v2
	v_mov_b32_e32 v91, v2
	v_mov_b32_e32 v92, v2
	v_mov_b32_e32 v93, v2
	v_mov_b32_e32 v94, v2
	v_mov_b32_e32 v95, v2
	v_mov_b32_e32 v96, v2
	v_mov_b32_e32 v97, v2
	v_mov_b32_e32 v106, v2
	v_mov_b32_e32 v107, v2
	v_mov_b32_e32 v108, v2
	v_mov_b32_e32 v109, v2
	v_mov_b32_e32 v110, v2
	v_mov_b32_e32 v111, v2
	v_mov_b32_e32 v112, v2
	v_mov_b32_e32 v113, v2
	v_mov_b32_e32 v122, v2
	v_mov_b32_e32 v123, v2
	v_mov_b32_e32 v124, v2
	v_mov_b32_e32 v125, v2
	v_mov_b32_e32 v126, v2
	v_mov_b32_e32 v127, v2
	v_mov_b32_e32 v128, v2
	v_mov_b32_e32 v129, v2
	v_add_u32_e32 v146, 0x80, v134
	v_add_u32_e32 v160, 0x80, v130
	v_add_u32_e32 v162, 0x80, v136
	v_add_u32_e32 v164, 0x80, v132
	v_add_u32_e32 v161, 0x10000, v148
.LBB0_302:
	s_add_u32 s22, s6, 0xfff80080
	s_addc_u32 s23, s7, -1
	s_add_i32 s59, 0, 0x10000
	ds_read_b128 v[142:145], v161
	ds_read_b128 v[152:155], v161 offset:1024
	ds_read_b128 v[156:159], v161 offset:2048
	ds_read_b128 v[174:177], v161 offset:3072
	s_cmp_eq_u32 s58, 28
	s_cselect_b32 s37, s15, s23
	s_cselect_b32 s36, s52, s22
	s_cselect_b32 s35, s13, s53
	s_cselect_b32 s34, s24, s25
	s_add_i32 m0, s28, 0xc000
	ds_read_b128 v[178:181], v150
	ds_read_b128 v[182:185], v150 offset:1024
	ds_read_b128 v[186:189], v150 offset:2048
	ds_read_b128 v[190:193], v150 offset:3072
	ds_read_b128 v[194:197], v150 offset:4096
	ds_read_b128 v[198:201], v150 offset:5120
	ds_read_b128 v[202:205], v150 offset:6144
	ds_read_b128 v[206:209], v150 offset:7168
	global_load_lds_dwordx4 v140, s[6:7]
	s_add_i32 m0, s28, 0xe000
	s_nop 0
	global_load_lds_dwordx4 v138, s[6:7]
	s_waitcnt lgkmcnt(8)
	s_barrier
	s_waitcnt lgkmcnt(0)
	s_waitcnt lgkmcnt(0)
	v_mfma_f32_16x16x32_f16 v[126:129], v[142:145], v[178:181], v[126:129]
	v_mfma_f32_16x16x32_f16 v[122:125], v[156:159], v[178:181], v[122:125]
	v_mfma_f32_16x16x32_f16 v[110:113], v[142:145], v[186:189], v[110:113]
	v_mfma_f32_16x16x32_f16 v[106:109], v[156:159], v[186:189], v[106:109]
	v_mfma_f32_16x16x32_f16 v[94:97], v[142:145], v[194:197], v[94:97]
	v_mfma_f32_16x16x32_f16 v[90:93], v[156:159], v[194:197], v[90:93]
	v_mfma_f32_16x16x32_f16 v[78:81], v[142:145], v[202:205], v[78:81]
	v_mfma_f32_16x16x32_f16 v[74:77], v[156:159], v[202:205], v[74:77]
	v_mfma_f32_16x16x32_f16 v[126:129], v[152:155], v[182:185], v[126:129]
	v_mfma_f32_16x16x32_f16 v[122:125], v[174:177], v[182:185], v[122:125]
	v_mfma_f32_16x16x32_f16 v[110:113], v[152:155], v[190:193], v[110:113]
	v_mfma_f32_16x16x32_f16 v[106:109], v[174:177], v[190:193], v[106:109]
	v_mfma_f32_16x16x32_f16 v[94:97], v[152:155], v[198:201], v[94:97]
	v_mfma_f32_16x16x32_f16 v[90:93], v[174:177], v[198:201], v[90:93]
	v_mfma_f32_16x16x32_f16 v[78:81], v[152:155], v[206:209], v[78:81]
	v_mfma_f32_16x16x32_f16 v[74:77], v[174:177], v[206:209], v[74:77]
	s_barrier
; #define PG8_STAGE(bufoff, gbase, voff) do { _Pragma("unroll") for (int _i = 0; _i < 2; ++_i) \
;         __builtin_amdgcn_global_load_lds((const unsigned*)((const char*)(gbase) + (voff)[_i]), (LAS unsigned*)(lds + (bufoff) + ldsw + _i * 8192), 16, 0, 0); } while (0)
; #define PG8_LDA(dst, b, h) do { _Pragma("unroll") for (int m = 0; m < 4; ++m) _Pragma("unroll") for (int k = 0; k < 2; ++k) dst[m][k] = *(const LAS f16x8*)(lds + PG8_SA(b, h) + aoff + m * 2048 + k * 1024); } while (0)
; #define PG8_LDB(dst, b, h) do { _Pragma("unroll") for (int n = 0; n < 2; ++n) _Pragma("unroll") for (int k = 0; k < 2; ++k) dst[n][k] = *(const LAS f16x8*)(lds + PG8_SB(b, h) + boff + n * 2048 + k * 1024); } while (0)
; #define PG8_MMA(ai, bj, At, Bt) do { __builtin_amdgcn_s_setprio(1); _Pragma("unroll") for (int m = 0; m < 4; ++m) _Pragma("unroll") for (int n = 0; n < 2; ++n) _Pragma("unroll") for (int k = 0; k < 2; ++k) \
;         acc[ai][bj][m][n] = __builtin_amdgcn_mfma_f32_16x16x32_f16(Bt[n][k], At[m][k], acc[ai][bj][m][n], 0, 0, 0); __builtin_amdgcn_s_setprio(0); } while (0)
; #define PG8_WAIT_V(n) asm volatile("s_waitcnt vmcnt(" #n ")" ::: "memory")
; #define PG8_WAIT_L(n) asm volatile("s_waitcnt lgkmcnt(" #n ")" ::: "memory")
; #define PG8_BAR __builtin_amdgcn_s_barrier()
; #define PG8_SCHED __builtin_amdgcn_sched_barrier(0)
; template <class Epi>
; __device__ __forceinline__ void gemm_phase(LAS unsigned char* lds, const Gemm g0, const StaticOrder& S, const Epi& E) {
;     ...
;             PG8_LDB(B1, 0, 1); PG8_STAGE(PG8_SB(0, 0), b2, voffB);
;             PG8_BAR; PG8_WAIT_L(0); PG8_MMA(0, 1, At, B1); PG8_BAR;
;             PG8_LDA(At, 0, 1); PG8_STAGE(PG8_SA(0, 0), a2, voffA);
;             PG8_BAR; PG8_WAIT_L(0); PG8_MMA(1, 0, At, B0); PG8_BAR; PG8_SCHED;
;             PG8_STAGE(PG8_SB(0, 1), b2 + hstep, voffB);
;             PG8_WAIT_V(6); PG8_BAR; PG8_MMA(1, 1, At, B1); PG8_BAR;
;             PG8_LDB(B0, 1, 0); PG8_SCHED; PG8_LDA(At, 1, 0); PG8_STAGE(PG8_SA(0, 1), a2 + hstep, voffA);
;             PG8_WAIT_L(8); PG8_BAR; PG8_WAIT_L(0); PG8_MMA(0, 0, At, B0); PG8_BAR; PG8_SCHED;
	s_add_i32 s61, 0, 0x14000
	s_add_i32 s22, s59, s19
	ds_read_b128 v[210:213], v161 offset:16384
	ds_read_b128 v[234:237], v161 offset:17408
	ds_read_b128 v[238:241], v161 offset:18432
	s_mov_b32 m0, s22
	ds_read_b128 v[242:245], v161 offset:19456
	global_load_lds_dwordx4 v134, s[34:35]
	s_add_i32 m0, s22, 0x2000
	s_nop 0
	global_load_lds_dwordx4 v130, s[34:35]
	s_barrier
	s_waitcnt lgkmcnt(0)
	s_waitcnt lgkmcnt(0)
	v_mfma_f32_16x16x32_f16 v[118:121], v[210:213], v[178:181], v[118:121]
	v_mfma_f32_16x16x32_f16 v[114:117], v[238:241], v[178:181], v[114:117]
	v_mfma_f32_16x16x32_f16 v[102:105], v[210:213], v[186:189], v[102:105]
	v_mfma_f32_16x16x32_f16 v[98:101], v[238:241], v[186:189], v[98:101]
	v_mfma_f32_16x16x32_f16 v[86:89], v[210:213], v[194:197], v[86:89]
	v_mfma_f32_16x16x32_f16 v[82:85], v[238:241], v[194:197], v[82:85]
	v_mfma_f32_16x16x32_f16 v[70:73], v[210:213], v[202:205], v[70:73]
	v_mfma_f32_16x16x32_f16 v[66:69], v[238:241], v[202:205], v[66:69]
	v_mfma_f32_16x16x32_f16 v[118:121], v[234:237], v[182:185], v[118:121]
	v_mfma_f32_16x16x32_f16 v[114:117], v[242:245], v[182:185], v[114:117]
	v_mfma_f32_16x16x32_f16 v[102:105], v[234:237], v[190:193], v[102:105]
	v_mfma_f32_16x16x32_f16 v[98:101], v[242:245], v[190:193], v[98:101]
	v_mfma_f32_16x16x32_f16 v[86:89], v[234:237], v[198:201], v[86:89]
	v_mfma_f32_16x16x32_f16 v[82:85], v[242:245], v[198:201], v[82:85]
	v_mfma_f32_16x16x32_f16 v[70:73], v[234:237], v[206:209], v[70:73]
	v_mfma_f32_16x16x32_f16 v[66:69], v[242:245], v[206:209], v[66:69]
	s_mov_b32 m0, s28
	s_barrier
	ds_read_b128 v[178:181], v150 offset:16384
	ds_read_b128 v[182:185], v150 offset:17408
	ds_read_b128 v[186:189], v150 offset:18432
	ds_read_b128 v[190:193], v150 offset:19456
	ds_read_b128 v[194:197], v150 offset:20480
	ds_read_b128 v[198:201], v150 offset:21504
	ds_read_b128 v[202:205], v150 offset:22528
	ds_read_b128 v[206:209], v150 offset:23552
	global_load_lds_dwordx4 v136, s[36:37]
	s_mov_b32 m0, s29
	s_nop 0
	global_load_lds_dwordx4 v132, s[36:37]
	s_barrier
	s_waitcnt lgkmcnt(0)
	s_waitcnt lgkmcnt(0)
	v_mfma_f32_16x16x32_f16 v[62:65], v[142:145], v[178:181], v[62:65]
	v_mfma_f32_16x16x32_f16 v[58:61], v[156:159], v[178:181], v[58:61]
	v_mfma_f32_16x16x32_f16 v[46:49], v[142:145], v[186:189], v[46:49]
	v_mfma_f32_16x16x32_f16 v[42:45], v[156:159], v[186:189], v[42:45]
	v_mfma_f32_16x16x32_f16 v[30:33], v[142:145], v[194:197], v[30:33]
	v_mfma_f32_16x16x32_f16 v[26:29], v[156:159], v[194:197], v[26:29]
	v_mfma_f32_16x16x32_f16 v[14:17], v[142:145], v[202:205], v[14:17]
	v_mfma_f32_16x16x32_f16 v[10:13], v[156:159], v[202:205], v[10:13]
	v_mfma_f32_16x16x32_f16 v[62:65], v[152:155], v[182:185], v[62:65]
	v_mfma_f32_16x16x32_f16 v[58:61], v[174:177], v[182:185], v[58:61]
	v_mfma_f32_16x16x32_f16 v[46:49], v[152:155], v[190:193], v[46:49]
	v_mfma_f32_16x16x32_f16 v[42:45], v[174:177], v[190:193], v[42:45]
	v_mfma_f32_16x16x32_f16 v[30:33], v[152:155], v[198:201], v[30:33]
	v_mfma_f32_16x16x32_f16 v[26:29], v[174:177], v[198:201], v[26:29]
	v_mfma_f32_16x16x32_f16 v[14:17], v[152:155], v[206:209], v[14:17]
	v_mfma_f32_16x16x32_f16 v[10:13], v[174:177], v[206:209], v[10:13]
	s_barrier
	s_add_u32 s22, s34, 0x80000
	s_addc_u32 s23, s35, 0
	s_add_i32 s59, s61, s19
	s_mov_b32 m0, s59
	s_nop 0
	global_load_lds_dwordx4 v134, s[22:23]
	s_add_i32 m0, s59, 0x2000
	s_nop 0
	global_load_lds_dwordx4 v130, s[22:23]
	s_waitcnt vmcnt(6)
	s_barrier
	v_mfma_f32_16x16x32_f16 v[54:57], v[210:213], v[178:181], v[54:57]
	v_mfma_f32_16x16x32_f16 v[50:53], v[238:241], v[178:181], v[50:53]
	v_mfma_f32_16x16x32_f16 v[38:41], v[210:213], v[186:189], v[38:41]
	v_mfma_f32_16x16x32_f16 v[34:37], v[238:241], v[186:189], v[34:37]
	v_mfma_f32_16x16x32_f16 v[22:25], v[210:213], v[194:197], v[22:25]
	v_mfma_f32_16x16x32_f16 v[18:21], v[238:241], v[194:197], v[18:21]
	v_mfma_f32_16x16x32_f16 v[6:9], v[210:213], v[202:205], v[6:9]
	v_mfma_f32_16x16x32_f16 v[2:5], v[238:241], v[202:205], v[2:5]
	v_mfma_f32_16x16x32_f16 v[54:57], v[234:237], v[182:185], v[54:57]
	v_mfma_f32_16x16x32_f16 v[50:53], v[242:245], v[182:185], v[50:53]
	v_mfma_f32_16x16x32_f16 v[38:41], v[234:237], v[190:193], v[38:41]
	v_mfma_f32_16x16x32_f16 v[34:37], v[242:245], v[190:193], v[34:37]
	v_mfma_f32_16x16x32_f16 v[22:25], v[234:237], v[198:201], v[22:25]
	v_mfma_f32_16x16x32_f16 v[18:21], v[242:245], v[198:201], v[18:21]
	v_mfma_f32_16x16x32_f16 v[6:9], v[234:237], v[206:209], v[6:9]
	v_mfma_f32_16x16x32_f16 v[2:5], v[242:245], v[206:209], v[2:5]
	s_add_i32 s59, 0, 0x18000
	s_barrier
	ds_read_b128 v[142:145], v161 offset:32768
	ds_read_b128 v[152:155], v161 offset:33792
	ds_read_b128 v[156:159], v161 offset:34816
	ds_read_b128 v[174:177], v161 offset:35840
	s_add_u32 s22, s36, 0x80000
	s_addc_u32 s23, s37, 0
	s_mov_b32 m0, s31
	ds_read_b128 v[178:181], v150 offset:32768
	ds_read_b128 v[182:185], v150 offset:33792
	ds_read_b128 v[186:189], v150 offset:34816
	ds_read_b128 v[190:193], v150 offset:35840
	ds_read_b128 v[194:197], v150 offset:36864
	ds_read_b128 v[198:201], v150 offset:37888
	ds_read_b128 v[202:205], v150 offset:38912
	ds_read_b128 v[206:209], v150 offset:39936
	global_load_lds_dwordx4 v136, s[22:23]
	s_mov_b32 m0, s38
	s_nop 0
	global_load_lds_dwordx4 v132, s[22:23]
	s_waitcnt lgkmcnt(8)
	s_barrier
; #define PG8_STAGE(bufoff, gbase, voff) do { _Pragma("unroll") for (int _i = 0; _i < 2; ++_i) \
;         __builtin_amdgcn_global_load_lds((const unsigned*)((const char*)(gbase) + (voff)[_i]), (LAS unsigned*)(lds + (bufoff) + ldsw + _i * 8192), 16, 0, 0); } while (0)
; #define PG8_LDA(dst, b, h) do { _Pragma("unroll") for (int m = 0; m < 4; ++m) _Pragma("unroll") for (int k = 0; k < 2; ++k) dst[m][k] = *(const LAS f16x8*)(lds + PG8_SA(b, h) + aoff + m * 2048 + k * 1024); } while (0)
; #define PG8_LDB(dst, b, h) do { _Pragma("unroll") for (int n = 0; n < 2; ++n) _Pragma("unroll") for (int k = 0; k < 2; ++k) dst[n][k] = *(const LAS f16x8*)(lds + PG8_SB(b, h) + boff + n * 2048 + k * 1024); } while (0)
; #define PG8_MMA(ai, bj, At, Bt) do { __builtin_amdgcn_s_setprio(1); _Pragma("unroll") for (int m = 0; m < 4; ++m) _Pragma("unroll") for (int n = 0; n < 2; ++n) _Pragma("unroll") for (int k = 0; k < 2; ++k) \
;         acc[ai][bj][m][n] = __builtin_amdgcn_mfma_f32_16x16x32_f16(Bt[n][k], At[m][k], acc[ai][bj][m][n], 0, 0, 0); __builtin_amdgcn_s_setprio(0); } while (0)
; #define PG8_WAIT_L(n) asm volatile("s_waitcnt lgkmcnt(" #n ")" ::: "memory")
; #define PG8_BAR __builtin_amdgcn_s_barrier()
; #define PG8_SCHED __builtin_amdgcn_sched_barrier(0)
; template <class Epi>
; __device__ __forceinline__ void gemm_phase(LAS unsigned char* lds, const Gemm g0, const StaticOrder& S, const Epi& E) {
;     ...
;             PG8_WAIT_L(8); PG8_BAR; PG8_WAIT_L(0); PG8_MMA(0, 0, At, B0); PG8_BAR; PG8_SCHED;
;             PG8_LDB(B1, 1, 1); PG8_STAGE(PG8_SB(1, 0), b3, voffB);
;             PG8_BAR; PG8_WAIT_L(0); PG8_MMA(0, 1, At, B1); PG8_BAR;
;             PG8_LDA(At, 1, 1); PG8_STAGE(PG8_SA(1, 0), a3, voffA);
;             PG8_BAR; PG8_WAIT_L(0); PG8_MMA(1, 0, At, B0); PG8_BAR; PG8_SCHED;
	s_waitcnt lgkmcnt(0)
	s_waitcnt lgkmcnt(0)
	v_mfma_f32_16x16x32_f16 v[126:129], v[142:145], v[178:181], v[126:129]
	v_mfma_f32_16x16x32_f16 v[122:125], v[156:159], v[178:181], v[122:125]
	v_mfma_f32_16x16x32_f16 v[110:113], v[142:145], v[186:189], v[110:113]
	v_mfma_f32_16x16x32_f16 v[106:109], v[156:159], v[186:189], v[106:109]
	v_mfma_f32_16x16x32_f16 v[94:97], v[142:145], v[194:197], v[94:97]
	v_mfma_f32_16x16x32_f16 v[90:93], v[156:159], v[194:197], v[90:93]
	v_mfma_f32_16x16x32_f16 v[78:81], v[142:145], v[202:205], v[78:81]
	v_mfma_f32_16x16x32_f16 v[74:77], v[156:159], v[202:205], v[74:77]
	v_mfma_f32_16x16x32_f16 v[126:129], v[152:155], v[182:185], v[126:129]
	v_mfma_f32_16x16x32_f16 v[122:125], v[174:177], v[182:185], v[122:125]
	v_mfma_f32_16x16x32_f16 v[110:113], v[152:155], v[190:193], v[110:113]
	v_mfma_f32_16x16x32_f16 v[106:109], v[174:177], v[190:193], v[106:109]
	v_mfma_f32_16x16x32_f16 v[94:97], v[152:155], v[198:201], v[94:97]
	v_mfma_f32_16x16x32_f16 v[90:93], v[174:177], v[198:201], v[90:93]
	v_mfma_f32_16x16x32_f16 v[78:81], v[152:155], v[206:209], v[78:81]
	v_mfma_f32_16x16x32_f16 v[74:77], v[174:177], v[206:209], v[74:77]
	s_barrier
	s_add_i32 s61, 0, 0x1c000
	s_add_i32 s22, s59, s19
	s_mov_b32 m0, s22
	ds_read_b128 v[210:213], v161 offset:49152
	ds_read_b128 v[234:237], v161 offset:50176
	ds_read_b128 v[238:241], v161 offset:51200
	ds_read_b128 v[242:245], v161 offset:52224
	global_load_lds_dwordx4 v146, s[34:35]
	s_add_i32 m0, s22, 0x2000
	s_nop 0
	global_load_lds_dwordx4 v160, s[34:35]
	s_barrier
	s_waitcnt lgkmcnt(0)
	s_waitcnt lgkmcnt(0)
	v_mfma_f32_16x16x32_f16 v[118:121], v[210:213], v[178:181], v[118:121]
	v_mfma_f32_16x16x32_f16 v[114:117], v[238:241], v[178:181], v[114:117]
	v_mfma_f32_16x16x32_f16 v[102:105], v[210:213], v[186:189], v[102:105]
	v_mfma_f32_16x16x32_f16 v[98:101], v[238:241], v[186:189], v[98:101]
	v_mfma_f32_16x16x32_f16 v[86:89], v[210:213], v[194:197], v[86:89]
	v_mfma_f32_16x16x32_f16 v[82:85], v[238:241], v[194:197], v[82:85]
	v_mfma_f32_16x16x32_f16 v[70:73], v[210:213], v[202:205], v[70:73]
	v_mfma_f32_16x16x32_f16 v[66:69], v[238:241], v[202:205], v[66:69]
	v_mfma_f32_16x16x32_f16 v[118:121], v[234:237], v[182:185], v[118:121]
	v_mfma_f32_16x16x32_f16 v[114:117], v[242:245], v[182:185], v[114:117]
	v_mfma_f32_16x16x32_f16 v[102:105], v[234:237], v[190:193], v[102:105]
	v_mfma_f32_16x16x32_f16 v[98:101], v[242:245], v[190:193], v[98:101]
	v_mfma_f32_16x16x32_f16 v[86:89], v[234:237], v[198:201], v[86:89]
	v_mfma_f32_16x16x32_f16 v[82:85], v[242:245], v[198:201], v[82:85]
	v_mfma_f32_16x16x32_f16 v[70:73], v[234:237], v[206:209], v[70:73]
	v_mfma_f32_16x16x32_f16 v[66:69], v[242:245], v[206:209], v[66:69]
	s_mov_b32 m0, s39
	s_barrier
	ds_read_b128 v[178:181], v150 offset:49152
	ds_read_b128 v[182:185], v150 offset:50176
	ds_read_b128 v[186:189], v150 offset:51200
	ds_read_b128 v[190:193], v150 offset:52224
	ds_read_b128 v[194:197], v150 offset:53248
	ds_read_b128 v[198:201], v150 offset:54272
	ds_read_b128 v[202:205], v150 offset:55296
	ds_read_b128 v[206:209], v150 offset:56320
	global_load_lds_dwordx4 v162, s[36:37]
	s_mov_b32 m0, s48
	s_nop 0
	global_load_lds_dwordx4 v164, s[36:37]
	s_barrier
	s_waitcnt lgkmcnt(0)
	s_waitcnt lgkmcnt(0)
	v_mfma_f32_16x16x32_f16 v[62:65], v[142:145], v[178:181], v[62:65]
	v_mfma_f32_16x16x32_f16 v[58:61], v[156:159], v[178:181], v[58:61]
	v_mfma_f32_16x16x32_f16 v[46:49], v[142:145], v[186:189], v[46:49]
	v_mfma_f32_16x16x32_f16 v[42:45], v[156:159], v[186:189], v[42:45]
	v_mfma_f32_16x16x32_f16 v[30:33], v[142:145], v[194:197], v[30:33]
	v_mfma_f32_16x16x32_f16 v[26:29], v[156:159], v[194:197], v[26:29]
	v_mfma_f32_16x16x32_f16 v[14:17], v[142:145], v[202:205], v[14:17]
	v_mfma_f32_16x16x32_f16 v[10:13], v[156:159], v[202:205], v[10:13]
	v_mfma_f32_16x16x32_f16 v[62:65], v[152:155], v[182:185], v[62:65]
	v_mfma_f32_16x16x32_f16 v[58:61], v[174:177], v[182:185], v[58:61]
	v_mfma_f32_16x16x32_f16 v[46:49], v[152:155], v[190:193], v[46:49]
	v_mfma_f32_16x16x32_f16 v[42:45], v[174:177], v[190:193], v[42:45]
	v_mfma_f32_16x16x32_f16 v[30:33], v[152:155], v[198:201], v[30:33]
	v_mfma_f32_16x16x32_f16 v[26:29], v[174:177], v[198:201], v[26:29]
	v_mfma_f32_16x16x32_f16 v[14:17], v[152:155], v[206:209], v[14:17]
	v_mfma_f32_16x16x32_f16 v[10:13], v[174:177], v[206:209], v[10:13]
	s_barrier
; __device__ __forceinline__ float gelu_tanh(float x) { const float y = 1.5957691216057308f * (x + 0.044715f * x * x * x); return x * fast_rcp(1.0f + __expf(-y)); }
; #define PG8_STAGE(bufoff, gbase, voff) do { _Pragma("unroll") for (int _i = 0; _i < 2; ++_i) \
;         __builtin_amdgcn_global_load_lds((const unsigned*)((const char*)(gbase) + (voff)[_i]), (LAS unsigned*)(lds + (bufoff) + ldsw + _i * 8192), 16, 0, 0); } while (0)
; #define PG8_MMA(ai, bj, At, Bt) do { __builtin_amdgcn_s_setprio(1); _Pragma("unroll") for (int m = 0; m < 4; ++m) _Pragma("unroll") for (int n = 0; n < 2; ++n) _Pragma("unroll") for (int k = 0; k < 2; ++k) \
;         acc[ai][bj][m][n] = __builtin_amdgcn_mfma_f32_16x16x32_f16(Bt[n][k], At[m][k], acc[ai][bj][m][n], 0, 0, 0); __builtin_amdgcn_s_setprio(0); } while (0)
; #define PG8_WAIT_V(n) asm volatile("s_waitcnt vmcnt(" #n ")" ::: "memory")
; #define PG8_BAR __builtin_amdgcn_s_barrier()
;     __device__ __forceinline__ void operator()(f32x4 (&acc)[2][2][4][2], const Unit& u, int wr, int wc, int fr, int fq) const {
;         const bool isy = u.pn < 8; h16* dst = isy ? ybr : xpre; const int colb = (isy ? u.pn : u.pn - 8) * BM + wc * 32 + 8 * fq;
;         const int row0 = u.pm * BM + wr * 64 + fr;
; #pragma unroll
;         for (int ai = 0; ai < 2; ++ai)
; #pragma unroll
;             for (int m = 0; m < 4; ++m) { h16* rowp = dst + (size_t)(row0 + ai * HALF + m * 16) * DM + colb;
; #pragma unroll
;                 for (int bj = 0; bj < 2; ++bj) { f32x4 v0 = acc[ai][bj][m][0], v1 = acc[ai][bj][m][1];
;                     if (isy) {
; #pragma unroll
;                         for (int j = 0; j < 4; ++j) { v0[j] = gelu_tanh(v0[j]); v1[j] = gelu_tanh(v1[j]); } }
; template <class Epi>
; __device__ __forceinline__ void gemm_phase(LAS unsigned char* lds, const Gemm g0, const StaticOrder& S, const Epi& E) {
;     ...
;             PG8_STAGE(PG8_SB(1, 1), b3 + hstep, voffB);
;             PG8_WAIT_V(6); PG8_BAR; PG8_MMA(1, 1, At, B1); PG8_BAR;
;         }
	s_add_u32 s22, s34, 0x80080
	s_addc_u32 s23, s35, 0
	s_add_i32 s34, s61, s19
	s_mov_b32 m0, s34
	s_nop 0
	global_load_lds_dwordx4 v134, s[22:23]
	s_add_i32 m0, s34, 0x2000
	s_nop 0
	global_load_lds_dwordx4 v130, s[22:23]
	s_waitcnt vmcnt(6)
	s_barrier
	v_mfma_f32_16x16x32_f16 v[54:57], v[210:213], v[178:181], v[54:57]
	v_mfma_f32_16x16x32_f16 v[50:53], v[238:241], v[178:181], v[50:53]
	v_mfma_f32_16x16x32_f16 v[38:41], v[210:213], v[186:189], v[38:41]
	v_mfma_f32_16x16x32_f16 v[34:37], v[238:241], v[186:189], v[34:37]
	v_mfma_f32_16x16x32_f16 v[22:25], v[210:213], v[194:197], v[22:25]
	v_mfma_f32_16x16x32_f16 v[18:21], v[238:241], v[194:197], v[18:21]
	v_mfma_f32_16x16x32_f16 v[6:9], v[210:213], v[202:205], v[6:9]
	v_mfma_f32_16x16x32_f16 v[2:5], v[238:241], v[202:205], v[2:5]
	v_mfma_f32_16x16x32_f16 v[54:57], v[234:237], v[182:185], v[54:57]
	v_mfma_f32_16x16x32_f16 v[50:53], v[242:245], v[182:185], v[50:53]
	v_mfma_f32_16x16x32_f16 v[38:41], v[234:237], v[190:193], v[38:41]
	v_mfma_f32_16x16x32_f16 v[34:37], v[242:245], v[190:193], v[34:37]
	v_mfma_f32_16x16x32_f16 v[22:25], v[234:237], v[198:201], v[22:25]
	v_mfma_f32_16x16x32_f16 v[18:21], v[242:245], v[198:201], v[18:21]
	v_mfma_f32_16x16x32_f16 v[6:9], v[234:237], v[206:209], v[6:9]
	v_mfma_f32_16x16x32_f16 v[2:5], v[242:245], v[206:209], v[2:5]
	s_add_i32 s58, s58, 2
	s_add_u32 s25, s25, 0x100
	s_addc_u32 s53, s53, 0
	s_add_u32 s6, s6, 0x100
	s_addc_u32 s7, s7, 0
	s_cmp_gt_u32 s58, 29
	s_barrier
	s_cbranch_scc0 .LBB0_302
	s_cmp_lt_i32 s51, 8
	s_cselect_b64 s[34:35], -1, 0
	s_cmp_gt_i32 s51, 7
	s_cbranch_scc1 .LBB0_305
	v_mul_f32_e32 v143, 0x3d372713, v122
	v_mul_f32_e32 v143, v122, v143
	v_fma_f32 v143, v122, v143, v122
	v_mul_f32_e32 v143, 0xbfcc422a, v143
	v_mul_f32_e32 v143, 0x3fb8aa3b, v143
	v_exp_f32_e32 v143, v143
	v_mul_f32_e32 v142, 0x3d372713, v126
	v_mul_f32_e32 v142, v126, v142
	v_fma_f32 v142, v126, v142, v126
	v_add_f32_e32 v143, 1.0, v143
	v_rcp_f32_e32 v144, v143
	v_mul_f32_e32 v143, 0x3d372713, v127
	v_mul_f32_e32 v143, v127, v143
	v_fma_f32 v143, v127, v143, v127
	v_mul_f32_e32 v142, 0xbfcc422a, v142
	v_mul_f32_e32 v143, 0xbfcc422a, v143
	v_mul_f32_e32 v142, 0x3fb8aa3b, v142
	v_mul_f32_e32 v143, 0x3fb8aa3b, v143
	v_mul_f32_e32 v147, 0x3d372713, v124
	v_exp_f32_e32 v142, v142
	v_exp_f32_e32 v143, v143
	v_mul_f32_e32 v147, v124, v147
	v_fma_f32 v147, v124, v147, v124
	v_mul_f32_e32 v147, 0xbfcc422a, v147
	v_mul_f32_e32 v147, 0x3fb8aa3b, v147
	v_add_f32_e32 v142, 1.0, v142
	v_add_f32_e32 v143, 1.0, v143
	v_exp_f32_e32 v147, v147
	v_rcp_f32_e32 v142, v142
	v_rcp_f32_e32 v143, v143
	v_mul_f32_e32 v145, 0x3d372713, v123
	v_add_f32_e32 v147, 1.0, v147
	v_mul_f32_e32 v146, 0x3d372713, v128
	v_rcp_f32_e32 v152, v147
	v_mul_f32_e32 v147, 0x3d372713, v129
	v_pk_mul_f32 v[126:127], v[126:127], v[142:143]
	v_mul_f32_e32 v142, 0x3d372713, v125
	v_mul_f32_e32 v145, v123, v145
	v_mul_f32_e32 v146, v128, v146
	v_mul_f32_e32 v147, v129, v147
	v_mul_f32_e32 v142, v125, v142
	v_fma_f32 v145, v123, v145, v123
	v_fma_f32 v146, v128, v146, v128
	v_fma_f32 v147, v129, v147, v129
	v_fma_f32 v142, v125, v142, v125
	v_mul_f32_e32 v145, 0xbfcc422a, v145
	v_mul_f32_e32 v146, 0xbfcc422a, v146
	v_mul_f32_e32 v147, 0xbfcc422a, v147
	v_mul_f32_e32 v142, 0xbfcc422a, v142
	v_mul_f32_e32 v145, 0x3fb8aa3b, v145
	v_mul_f32_e32 v146, 0x3fb8aa3b, v146
	v_mul_f32_e32 v147, 0x3fb8aa3b, v147
	v_mul_f32_e32 v142, 0x3fb8aa3b, v142
	v_exp_f32_e32 v145, v145
	v_exp_f32_e32 v146, v146
	v_exp_f32_e32 v147, v147
	v_exp_f32_e32 v142, v142
	v_add_f32_e32 v145, 1.0, v145
	v_add_f32_e32 v146, 1.0, v146
	v_add_f32_e32 v147, 1.0, v147
	v_add_f32_e32 v142, 1.0, v142
	v_rcp_f32_e32 v145, v145
	v_rcp_f32_e32 v146, v146
	v_rcp_f32_e32 v147, v147
	v_rcp_f32_e32 v153, v142
	v_pk_mul_f32 v[122:123], v[122:123], v[144:145]
	v_pk_mul_f32 v[128:129], v[128:129], v[146:147]
	v_pk_mul_f32 v[124:125], v[124:125], v[152:153]

;     __device__ __forceinline__ void prefetch(const Unit& u, int wr, int wc, int lane) const { lnfold_prefetch(vl, stats, gW, bW, u, wr, wc, lane); }
;     __device__ __forceinline__ void prefetch(const Unit& u, int wr, int wc, int lane) const { lnfold_prefetch(vl, stats, gW, bW, u, wr, wc, lane); }
; #define PG8_STAGE(bufoff, gbase, voff) do { _Pragma("unroll") for (int _i = 0; _i < 2; ++_i) \
;         __builtin_amdgcn_global_load_lds((const unsigned*)((const char*)(gbase) + (voff)[_i]), (LAS unsigned*)(lds + (bufoff) + ldsw + _i * 8192), 16, 0, 0); } while (0)
; #define PG8_LDA(dst, b, h) do { _Pragma("unroll") for (int m = 0; m < 4; ++m) _Pragma("unroll") for (int k = 0; k < 2; ++k) dst[m][k] = *(const LAS f16x8*)(lds + PG8_SA(b, h) + aoff + m * 2048 + k * 1024); } while (0)
; #define PG8_LDB(dst, b, h) do { _Pragma("unroll") for (int n = 0; n < 2; ++n) _Pragma("unroll") for (int k = 0; k < 2; ++k) dst[n][k] = *(const LAS f16x8*)(lds + PG8_SB(b, h) + boff + n * 2048 + k * 1024); } while (0)
; #define PG8_BAR __builtin_amdgcn_s_barrier()
; template <class Epi>
; __device__ __forceinline__ void gemm_phase(LAS unsigned char* lds, const Gemm g0, const StaticOrder& S, const Epi& E) {
;     ...
;         const bool has_next = S.next(ui + 1, nxt);
;         const char* nA = has_next ? (const char*)g.A + (size_t)nxt.pm * tstep : cA; const char* nB = has_next ? (const char*)g.Bt + (size_t)nxt.pn * tstep : cB;
;         for (int t = 0; t < nt; t += 2) {
;             const bool last = (t == nt - 2);
;             if (Epi::PREF && last) E.prefetch(cur, wr, wc, lane);
;             const char* a1 = cA + (size_t)(t + 1) * kstep;
;             const char* a2 = last ? nA : cA + (size_t)(t + 2) * kstep; const char* b2 = last ? nB : cB + (size_t)(t + 2) * kstep;
;             const char* a3 = a2 + kstep; const char* b3 = b2 + kstep;
;             PG8_LDB(B0, 0, 0); PG8_SCHED; PG8_LDA(At, 0, 0); PG8_STAGE(PG8_SA(1, 1), a1 + hstep, voffA);
;             PG8_WAIT_L(8); PG8_BAR; PG8_WAIT_L(0); PG8_MMA(0, 0, At, B0); PG8_BAR; PG8_SCHED;
;     ...
; #pragma unroll
;         for (int a = 0; a < 2; ++a)
; #pragma unroll
;             for (int b = 0; b < 2; ++b)
; #pragma unroll
;                 for (int m = 0; m < 4; ++m)
; #pragma unroll
;                     for (int n = 0; n < 2; ++n) acc[a][b][m][n] = (f32x4){0.f, 0.f, 0.f, 0.f};
;         cur = nxt; cA = nA; cB = nB; ++ui;
.LBB0_511:
	s_ashr_i32 s15, s14, 31
	s_lshl_b64 s[22:23], s[14:15], 20
	v_cmp_lt_i64_e32 vcc, s[36:37], v[168:169]
	s_add_u32 s36, s92, s22
	s_addc_u32 s37, s93, s23
	s_and_b64 s[22:23], vcc, exec
	s_cselect_b32 s15, s37, s49
	s_cselect_b32 s24, s36, s48
	s_ashr_i32 s53, s52, 31
	s_lshl_b64 s[22:23], s[52:53], 20
	s_add_u32 s38, s96, s22
	s_addc_u32 s39, s97, s23
	s_and_b64 s[22:23], vcc, exec
	s_cselect_b32 s25, s39, s13
	s_cselect_b32 s53, s38, s12
	s_add_u32 vcc_lo, s12, 0x100
	s_addc_u32 vcc_hi, s13, 0
	s_add_u32 s12, s48, 0x80080
	v_mov_b32_e32 v2, 0
	s_addc_u32 s13, s49, 0
	s_mov_b32 s22, -2
	v_mov_b32_e32 v3, v2
	v_mov_b32_e32 v4, v2
	v_mov_b32_e32 v5, v2
	v_mov_b32_e32 v6, v2
	v_mov_b32_e32 v7, v2
	v_mov_b32_e32 v8, v2
	v_mov_b32_e32 v9, v2
	v_mov_b32_e32 v18, v2
	v_mov_b32_e32 v19, v2
	v_mov_b32_e32 v20, v2
	v_mov_b32_e32 v21, v2
	v_mov_b32_e32 v22, v2
	v_mov_b32_e32 v23, v2
	v_mov_b32_e32 v24, v2
	v_mov_b32_e32 v25, v2
	v_mov_b32_e32 v34, v2
	v_mov_b32_e32 v35, v2
	v_mov_b32_e32 v36, v2
	v_mov_b32_e32 v37, v2
	v_mov_b32_e32 v38, v2
	v_mov_b32_e32 v39, v2
	v_mov_b32_e32 v40, v2
	v_mov_b32_e32 v41, v2
	v_mov_b32_e32 v50, v2
	v_mov_b32_e32 v51, v2
	v_mov_b32_e32 v52, v2
	v_mov_b32_e32 v53, v2
	v_mov_b32_e32 v54, v2
	v_mov_b32_e32 v55, v2
	v_mov_b32_e32 v56, v2
	v_mov_b32_e32 v57, v2
	v_mov_b32_e32 v10, v2
	v_mov_b32_e32 v11, v2
	v_mov_b32_e32 v12, v2
	v_mov_b32_e32 v13, v2
	v_mov_b32_e32 v14, v2
	v_mov_b32_e32 v15, v2
	v_mov_b32_e32 v16, v2
	v_mov_b32_e32 v17, v2
	v_mov_b32_e32 v26, v2
	v_mov_b32_e32 v27, v2
	v_mov_b32_e32 v28, v2
	v_mov_b32_e32 v29, v2
	v_mov_b32_e32 v30, v2
	v_mov_b32_e32 v31, v2
	v_mov_b32_e32 v32, v2
	v_mov_b32_e32 v33, v2
	v_mov_b32_e32 v42, v2
	v_mov_b32_e32 v43, v2
	v_mov_b32_e32 v44, v2
	v_mov_b32_e32 v45, v2
	v_mov_b32_e32 v46, v2
	v_mov_b32_e32 v47, v2
	v_mov_b32_e32 v48, v2
	v_mov_b32_e32 v49, v2
	v_mov_b32_e32 v58, v2
	v_mov_b32_e32 v59, v2
	v_mov_b32_e32 v60, v2
	v_mov_b32_e32 v61, v2
	v_mov_b32_e32 v62, v2
	v_mov_b32_e32 v63, v2
	v_mov_b32_e32 v64, v2
	v_mov_b32_e32 v65, v2
	v_mov_b32_e32 v66, v2
	v_mov_b32_e32 v67, v2
	v_mov_b32_e32 v68, v2
	v_mov_b32_e32 v69, v2
	v_mov_b32_e32 v70, v2
	v_mov_b32_e32 v71, v2
	v_mov_b32_e32 v72, v2
	v_mov_b32_e32 v73, v2
	v_mov_b32_e32 v82, v2
	v_mov_b32_e32 v83, v2
	v_mov_b32_e32 v84, v2
	v_mov_b32_e32 v85, v2
	v_mov_b32_e32 v86, v2
	v_mov_b32_e32 v87, v2
	v_mov_b32_e32 v88, v2
	v_mov_b32_e32 v89, v2
	v_mov_b32_e32 v98, v2
	v_mov_b32_e32 v99, v2
	s_waitcnt vmcnt(0)
	v_mov_b32_e32 v100, v2
	v_mov_b32_e32 v101, v2
	v_mov_b32_e32 v102, v2
	v_mov_b32_e32 v103, v2
	v_mov_b32_e32 v104, v2
	v_mov_b32_e32 v105, v2
	v_mov_b32_e32 v114, v2
	v_mov_b32_e32 v115, v2
	v_mov_b32_e32 v116, v2
	v_mov_b32_e32 v117, v2
	v_mov_b32_e32 v118, v2
	v_mov_b32_e32 v119, v2
	v_mov_b32_e32 v120, v2
	v_mov_b32_e32 v121, v2
	v_mov_b32_e32 v74, v2
	v_mov_b32_e32 v75, v2
	v_mov_b32_e32 v76, v2
	v_mov_b32_e32 v77, v2
	v_mov_b32_e32 v78, v2
	v_mov_b32_e32 v79, v2
	v_mov_b32_e32 v80, v2
	v_mov_b32_e32 v81, v2
	v_mov_b32_e32 v90, v2
	v_mov_b32_e32 v91, v2
	v_mov_b32_e32 v92, v2
	v_mov_b32_e32 v93, v2
	v_mov_b32_e32 v94, v2
	v_mov_b32_e32 v95, v2
	v_mov_b32_e32 v96, v2
	v_mov_b32_e32 v97, v2
	v_mov_b32_e32 v106, v2
	v_mov_b32_e32 v107, v2
	v_mov_b32_e32 v108, v2
	v_mov_b32_e32 v109, v2
	v_mov_b32_e32 v110, v2
	v_mov_b32_e32 v111, v2
	v_mov_b32_e32 v112, v2
	v_mov_b32_e32 v113, v2
	v_mov_b32_e32 v130, v2
	v_mov_b32_e32 v131, v2
	v_mov_b32_e32 v132, v2
	v_mov_b32_e32 v133, v2
	v_mov_b32_e32 v134, v2
	v_mov_b32_e32 v135, v2
	v_mov_b32_e32 v136, v2
	v_mov_b32_e32 v137, v2
	v_add_u32_e32 v164, 0x80, v174
	v_add_u32_e32 v165, 0x10000, v205
.LBB0_512:
	s_add_u32 s23, s12, 0xfff80080
	s_addc_u32 s48, s13, -1
	s_add_i32 s90, 0, 0x10000
	ds_read_b128 v[122:125], v165
	ds_read_b128 v[126:129], v165 offset:1024
	ds_read_b128 v[138:141], v165 offset:2048
	ds_read_b128 v[142:145], v165 offset:3072
	s_cmp_eq_u32 s22, 28
	s_cselect_b32 s51, s15, s48
	s_cselect_b32 s50, s24, s23
	s_cselect_b32 s49, s25, vcc_hi
	s_cselect_b32 s48, s53, vcc_lo
	s_add_i32 m0, s71, 0xc000
	ds_read_b128 v[146:149], v210
	ds_read_b128 v[150:153], v210 offset:1024
	ds_read_b128 v[154:157], v210 offset:2048
	ds_read_b128 v[158:161], v210 offset:3072
	ds_read_b128 v[188:191], v210 offset:4096
	ds_read_b128 v[192:195], v210 offset:5120
	ds_read_b128 v[196:199], v210 offset:6144
	ds_read_b128 v[200:203], v210 offset:7168
	global_load_lds_dwordx4 v186, s[12:13]
	s_add_i32 m0, s71, 0xe000
	s_nop 0
	global_load_lds_dwordx4 v184, s[12:13]
	s_waitcnt lgkmcnt(8)
	s_barrier
	s_waitcnt lgkmcnt(0)
	s_waitcnt lgkmcnt(0)
	v_mfma_f32_16x16x32_f16 v[134:137], v[122:125], v[146:149], v[134:137]
	v_mfma_f32_16x16x32_f16 v[130:133], v[138:141], v[146:149], v[130:133]
	v_mfma_f32_16x16x32_f16 v[110:113], v[122:125], v[154:157], v[110:113]
	v_mfma_f32_16x16x32_f16 v[106:109], v[138:141], v[154:157], v[106:109]
	v_mfma_f32_16x16x32_f16 v[94:97], v[122:125], v[188:191], v[94:97]
	v_mfma_f32_16x16x32_f16 v[90:93], v[138:141], v[188:191], v[90:93]
	v_mfma_f32_16x16x32_f16 v[78:81], v[122:125], v[196:199], v[78:81]
	v_mfma_f32_16x16x32_f16 v[74:77], v[138:141], v[196:199], v[74:77]
	v_mfma_f32_16x16x32_f16 v[134:137], v[126:129], v[150:153], v[134:137]
	v_mfma_f32_16x16x32_f16 v[130:133], v[142:145], v[150:153], v[130:133]
	v_mfma_f32_16x16x32_f16 v[110:113], v[126:129], v[158:161], v[110:113]
	v_mfma_f32_16x16x32_f16 v[106:109], v[142:145], v[158:161], v[106:109]
	v_mfma_f32_16x16x32_f16 v[94:97], v[126:129], v[192:195], v[94:97]
	v_mfma_f32_16x16x32_f16 v[90:93], v[142:145], v[192:195], v[90:93]
	v_mfma_f32_16x16x32_f16 v[78:81], v[126:129], v[200:203], v[78:81]
	v_mfma_f32_16x16x32_f16 v[74:77], v[142:145], v[200:203], v[74:77]
	s_barrier
; #define PG8_STAGE(bufoff, gbase, voff) do { _Pragma("unroll") for (int _i = 0; _i < 2; ++_i) \
;         __builtin_amdgcn_global_load_lds((const unsigned*)((const char*)(gbase) + (voff)[_i]), (LAS unsigned*)(lds + (bufoff) + ldsw + _i * 8192), 16, 0, 0); } while (0)
; #define PG8_LDA(dst, b, h) do { _Pragma("unroll") for (int m = 0; m < 4; ++m) _Pragma("unroll") for (int k = 0; k < 2; ++k) dst[m][k] = *(const LAS f16x8*)(lds + PG8_SA(b, h) + aoff + m * 2048 + k * 1024); } while (0)
; #define PG8_LDB(dst, b, h) do { _Pragma("unroll") for (int n = 0; n < 2; ++n) _Pragma("unroll") for (int k = 0; k < 2; ++k) dst[n][k] = *(const LAS f16x8*)(lds + PG8_SB(b, h) + boff + n * 2048 + k * 1024); } while (0)
; #define PG8_MMA(ai, bj, At, Bt) do { __builtin_amdgcn_s_setprio(1); _Pragma("unroll") for (int m = 0; m < 4; ++m) _Pragma("unroll") for (int n = 0; n < 2; ++n) _Pragma("unroll") for (int k = 0; k < 2; ++k) \
;         acc[ai][bj][m][n] = __builtin_amdgcn_mfma_f32_16x16x32_f16(Bt[n][k], At[m][k], acc[ai][bj][m][n], 0, 0, 0); __builtin_amdgcn_s_setprio(0); } while (0)
; #define PG8_WAIT_V(n) asm volatile("s_waitcnt vmcnt(" #n ")" ::: "memory")
; #define PG8_WAIT_L(n) asm volatile("s_waitcnt lgkmcnt(" #n ")" ::: "memory")
; #define PG8_BAR __builtin_amdgcn_s_barrier()
; #define PG8_SCHED __builtin_amdgcn_sched_barrier(0)
; template <class Epi>
; __device__ __forceinline__ void gemm_phase(LAS unsigned char* lds, const Gemm g0, const StaticOrder& S, const Epi& E) {
;     ...
;             PG8_LDB(B1, 0, 1); PG8_STAGE(PG8_SB(0, 0), b2, voffB);
;             PG8_BAR; PG8_WAIT_L(0); PG8_MMA(0, 1, At, B1); PG8_BAR;
;             PG8_LDA(At, 0, 1); PG8_STAGE(PG8_SA(0, 0), a2, voffA);
;             PG8_BAR; PG8_WAIT_L(0); PG8_MMA(1, 0, At, B0); PG8_BAR; PG8_SCHED;
;             PG8_STAGE(PG8_SB(0, 1), b2 + hstep, voffB);
;             PG8_WAIT_V(6); PG8_BAR; PG8_MMA(1, 1, At, B1); PG8_BAR;
;             PG8_LDB(B0, 1, 0); PG8_SCHED; PG8_LDA(At, 1, 0); PG8_STAGE(PG8_SA(0, 1), a2 + hstep, voffA);
;             PG8_WAIT_L(8); PG8_BAR; PG8_WAIT_L(0); PG8_MMA(0, 0, At, B0); PG8_BAR; PG8_SCHED;
	s_add_i32 s23, 0, 0x14000
	s_add_i32 s90, s90, s75
	ds_read_b128 v[212:215], v165 offset:16384
	ds_read_b128 v[234:237], v165 offset:17408
	ds_read_b128 v[238:241], v165 offset:18432
	ds_read_b128 v[242:245], v165 offset:19456
	v_add_u32_e32 v162, 0x80, v178
	s_mov_b32 m0, s90
	s_nop 0
	global_load_lds_dwordx4 v178, s[48:49]
	s_add_i32 m0, s90, 0x2000
	s_nop 0
	global_load_lds_dwordx4 v174, s[48:49]
	s_barrier
	s_waitcnt lgkmcnt(0)
	s_waitcnt lgkmcnt(0)
	v_mfma_f32_16x16x32_f16 v[118:121], v[212:215], v[146:149], v[118:121]
	v_mfma_f32_16x16x32_f16 v[114:117], v[238:241], v[146:149], v[114:117]
	v_mfma_f32_16x16x32_f16 v[102:105], v[212:215], v[154:157], v[102:105]
	v_mfma_f32_16x16x32_f16 v[98:101], v[238:241], v[154:157], v[98:101]
	v_mfma_f32_16x16x32_f16 v[86:89], v[212:215], v[188:191], v[86:89]
	v_mfma_f32_16x16x32_f16 v[82:85], v[238:241], v[188:191], v[82:85]
	v_mfma_f32_16x16x32_f16 v[70:73], v[212:215], v[196:199], v[70:73]
	v_mfma_f32_16x16x32_f16 v[66:69], v[238:241], v[196:199], v[66:69]
	v_mfma_f32_16x16x32_f16 v[118:121], v[234:237], v[150:153], v[118:121]
	v_mfma_f32_16x16x32_f16 v[114:117], v[242:245], v[150:153], v[114:117]
	v_mfma_f32_16x16x32_f16 v[102:105], v[234:237], v[158:161], v[102:105]
	v_mfma_f32_16x16x32_f16 v[98:101], v[242:245], v[158:161], v[98:101]
	v_mfma_f32_16x16x32_f16 v[86:89], v[234:237], v[192:195], v[86:89]
	v_mfma_f32_16x16x32_f16 v[82:85], v[242:245], v[192:195], v[82:85]
	v_mfma_f32_16x16x32_f16 v[70:73], v[234:237], v[200:203], v[70:73]
	v_mfma_f32_16x16x32_f16 v[66:69], v[242:245], v[200:203], v[66:69]
	s_mov_b32 m0, s71
	v_lshl_add_u64 v[170:171], s[50:51], 0, v[180:181]
	s_barrier
	ds_read_b128 v[146:149], v210 offset:16384
	ds_read_b128 v[150:153], v210 offset:17408
	ds_read_b128 v[154:157], v210 offset:18432
	ds_read_b128 v[158:161], v210 offset:19456
	ds_read_b128 v[188:191], v210 offset:20480
	ds_read_b128 v[192:195], v210 offset:21504
	ds_read_b128 v[196:199], v210 offset:22528
	ds_read_b128 v[200:203], v210 offset:23552
	global_load_lds_dwordx4 v[170:171], off
	v_lshl_add_u64 v[172:173], s[50:51], 0, v[176:177]
	s_mov_b32 m0, s61
	s_nop 0
	global_load_lds_dwordx4 v[172:173], off
	s_barrier
	s_waitcnt lgkmcnt(0)
	s_waitcnt lgkmcnt(0)
	v_mfma_f32_16x16x32_f16 v[62:65], v[122:125], v[146:149], v[62:65]
	v_mfma_f32_16x16x32_f16 v[58:61], v[138:141], v[146:149], v[58:61]
	v_mfma_f32_16x16x32_f16 v[46:49], v[122:125], v[154:157], v[46:49]
	v_mfma_f32_16x16x32_f16 v[42:45], v[138:141], v[154:157], v[42:45]
	v_mfma_f32_16x16x32_f16 v[30:33], v[122:125], v[188:191], v[30:33]
	v_mfma_f32_16x16x32_f16 v[26:29], v[138:141], v[188:191], v[26:29]
	v_mfma_f32_16x16x32_f16 v[14:17], v[122:125], v[196:199], v[14:17]
	v_mfma_f32_16x16x32_f16 v[10:13], v[138:141], v[196:199], v[10:13]
	v_mfma_f32_16x16x32_f16 v[62:65], v[126:129], v[150:153], v[62:65]
	v_mfma_f32_16x16x32_f16 v[58:61], v[142:145], v[150:153], v[58:61]
	v_mfma_f32_16x16x32_f16 v[46:49], v[126:129], v[158:161], v[46:49]
	v_mfma_f32_16x16x32_f16 v[42:45], v[142:145], v[158:161], v[42:45]
	v_mfma_f32_16x16x32_f16 v[30:33], v[126:129], v[192:195], v[30:33]
	v_mfma_f32_16x16x32_f16 v[26:29], v[142:145], v[192:195], v[26:29]
	v_mfma_f32_16x16x32_f16 v[14:17], v[126:129], v[200:203], v[14:17]
	v_mfma_f32_16x16x32_f16 v[10:13], v[142:145], v[200:203], v[10:13]
	s_barrier
	s_add_u32 s90, s48, 0x80000
	s_addc_u32 s91, s49, 0
	s_add_i32 s23, s23, s75
	s_mov_b32 m0, s23
	s_nop 0
	global_load_lds_dwordx4 v178, s[90:91]
	s_add_i32 m0, s23, 0x2000
	s_nop 0
	global_load_lds_dwordx4 v174, s[90:91]
	s_waitcnt vmcnt(6)
	s_barrier
	v_mfma_f32_16x16x32_f16 v[54:57], v[212:215], v[146:149], v[54:57]
	v_mfma_f32_16x16x32_f16 v[50:53], v[238:241], v[146:149], v[50:53]
	v_mfma_f32_16x16x32_f16 v[38:41], v[212:215], v[154:157], v[38:41]
	v_mfma_f32_16x16x32_f16 v[34:37], v[238:241], v[154:157], v[34:37]
	v_mfma_f32_16x16x32_f16 v[22:25], v[212:215], v[188:191], v[22:25]
	v_mfma_f32_16x16x32_f16 v[18:21], v[238:241], v[188:191], v[18:21]
	v_mfma_f32_16x16x32_f16 v[6:9], v[212:215], v[196:199], v[6:9]
	v_mfma_f32_16x16x32_f16 v[2:5], v[238:241], v[196:199], v[2:5]
	v_mfma_f32_16x16x32_f16 v[54:57], v[234:237], v[150:153], v[54:57]
	v_mfma_f32_16x16x32_f16 v[50:53], v[242:245], v[150:153], v[50:53]
	v_mfma_f32_16x16x32_f16 v[38:41], v[234:237], v[158:161], v[38:41]
	v_mfma_f32_16x16x32_f16 v[34:37], v[242:245], v[158:161], v[34:37]
	v_mfma_f32_16x16x32_f16 v[22:25], v[234:237], v[192:195], v[22:25]
	v_mfma_f32_16x16x32_f16 v[18:21], v[242:245], v[192:195], v[18:21]
	v_mfma_f32_16x16x32_f16 v[6:9], v[234:237], v[200:203], v[6:9]
	v_mfma_f32_16x16x32_f16 v[2:5], v[242:245], v[200:203], v[2:5]
	s_add_i32 s23, 0, 0x18000
	s_barrier
	ds_read_b128 v[122:125], v165 offset:32768
	ds_read_b128 v[126:129], v165 offset:33792
	ds_read_b128 v[138:141], v165 offset:34816
	ds_read_b128 v[142:145], v165 offset:35840
	s_add_u32 s50, s50, 0x80000
	s_addc_u32 s51, s51, 0
	s_mov_b32 m0, s74
	ds_read_b128 v[146:149], v210 offset:32768
	ds_read_b128 v[150:153], v210 offset:33792
	ds_read_b128 v[154:157], v210 offset:34816
	ds_read_b128 v[158:161], v210 offset:35840
	ds_read_b128 v[188:191], v210 offset:36864
	ds_read_b128 v[192:195], v210 offset:37888
	ds_read_b128 v[196:199], v210 offset:38912
	ds_read_b128 v[200:203], v210 offset:39936
	global_load_lds_dwordx4 v180, s[50:51]
	s_mov_b32 m0, s18
	s_nop 0
	global_load_lds_dwordx4 v176, s[50:51]
	s_waitcnt lgkmcnt(8)
	s_barrier
; #define LAS __attribute__((address_space(3)))
; #define GAS __attribute__((address_space(1)))
; #define PG8_STAGE(bufoff, gbase, voff) do { _Pragma("unroll") for (int _i = 0; _i < 2; ++_i) \
;         __builtin_amdgcn_global_load_lds((const unsigned*)((const char*)(gbase) + (voff)[_i]), (LAS unsigned*)(lds + (bufoff) + ldsw + _i * 8192), 16, 0, 0); } while (0)
; #define PG8_LDA(dst, b, h) do { _Pragma("unroll") for (int m = 0; m < 4; ++m) _Pragma("unroll") for (int k = 0; k < 2; ++k) dst[m][k] = *(const LAS f16x8*)(lds + PG8_SA(b, h) + aoff + m * 2048 + k * 1024); } while (0)
; #define PG8_LDB(dst, b, h) do { _Pragma("unroll") for (int n = 0; n < 2; ++n) _Pragma("unroll") for (int k = 0; k < 2; ++k) dst[n][k] = *(const LAS f16x8*)(lds + PG8_SB(b, h) + boff + n * 2048 + k * 1024); } while (0)
; #define PG8_WAIT_V(n) asm volatile("s_waitcnt vmcnt(" #n ")" ::: "memory")
; #define PG8_WAIT_L(n) asm volatile("s_waitcnt lgkmcnt(" #n ")" ::: "memory")
; #define PG8_BAR __builtin_amdgcn_s_barrier()
;     __device__ __forceinline__ void operator()(f32x4 (&acc)[2][2][4][2], const Unit& u, int wr, int wc, int fr, int fq) const {
;         const int row0 = u.pm * BM + wr * 64 + fr, colb = u.pn * BM + wc * 32 + 8 * fq;
;         const bool hasln = pstats != nullptr, haszh = zh != nullptr;
;         LAS float* slot = vl + (wr * 4 + wc) * 256;
;         f32x4 rn[2][2]; float ssm[8], ssq[8]; f32x2 stn = {0.f, 0.f};
;         { const int lane = fr + 16 * fq, cL = u.pn * BM + wc * 32 + (lane < 32 ? lane : 96 + lane);
;           float vg = 0.f, vb = 0.f, vt = 0.f;
;           if (hasln) { vg = *(const GAS float*)(pg + cL); vb = *(const GAS float*)(pb + cL); }
;           if (haszh) vt = *(const GAS float*)(tg + cL);
; template <class Epi>
; __device__ __forceinline__ void gemm_phase(LAS unsigned char* lds, const Gemm g0, const StaticOrder& S, const Epi& E) {
;     ...
;             PG8_WAIT_L(8); PG8_BAR; PG8_WAIT_L(0); PG8_MMA(0, 0, At, B0); PG8_BAR; PG8_SCHED;
;             PG8_LDB(B1, 1, 1); PG8_STAGE(PG8_SB(1, 0), b3, voffB);
;             PG8_BAR; PG8_WAIT_L(0); PG8_MMA(0, 1, At, B1); PG8_BAR;
;             PG8_LDA(At, 1, 1); PG8_STAGE(PG8_SA(1, 0), a3, voffA);
;             PG8_BAR; PG8_WAIT_L(0); PG8_MMA(1, 0, At, B0); PG8_BAR; PG8_SCHED;
;             PG8_STAGE(PG8_SB(1, 1), b3 + hstep, voffB);
;             PG8_WAIT_V(6); PG8_BAR; PG8_MMA(1, 1, At, B1); PG8_BAR;
;         }
	s_waitcnt lgkmcnt(0)
	s_waitcnt lgkmcnt(0)
	v_mfma_f32_16x16x32_f16 v[134:137], v[122:125], v[146:149], v[134:137]
	v_mfma_f32_16x16x32_f16 v[130:133], v[138:141], v[146:149], v[130:133]
	v_mfma_f32_16x16x32_f16 v[110:113], v[122:125], v[154:157], v[110:113]
	v_mfma_f32_16x16x32_f16 v[106:109], v[138:141], v[154:157], v[106:109]
	v_mfma_f32_16x16x32_f16 v[94:97], v[122:125], v[188:191], v[94:97]
	v_mfma_f32_16x16x32_f16 v[90:93], v[138:141], v[188:191], v[90:93]
	v_mfma_f32_16x16x32_f16 v[78:81], v[122:125], v[196:199], v[78:81]
	v_mfma_f32_16x16x32_f16 v[74:77], v[138:141], v[196:199], v[74:77]
	v_mfma_f32_16x16x32_f16 v[134:137], v[126:129], v[150:153], v[134:137]
	v_mfma_f32_16x16x32_f16 v[130:133], v[142:145], v[150:153], v[130:133]
	v_mfma_f32_16x16x32_f16 v[110:113], v[126:129], v[158:161], v[110:113]
	v_mfma_f32_16x16x32_f16 v[106:109], v[142:145], v[158:161], v[106:109]
	v_mfma_f32_16x16x32_f16 v[94:97], v[126:129], v[192:195], v[94:97]
	v_mfma_f32_16x16x32_f16 v[90:93], v[142:145], v[192:195], v[90:93]
	v_mfma_f32_16x16x32_f16 v[78:81], v[126:129], v[200:203], v[78:81]
	v_mfma_f32_16x16x32_f16 v[74:77], v[142:145], v[200:203], v[74:77]
	s_barrier
	s_add_i32 s50, 0, 0x1c000
	s_add_i32 s23, s23, s75
	s_mov_b32 m0, s23
	ds_read_b128 v[212:215], v165 offset:49152
	ds_read_b128 v[234:237], v165 offset:50176
	ds_read_b128 v[238:241], v165 offset:51200
	ds_read_b128 v[242:245], v165 offset:52224
	global_load_lds_dwordx4 v162, s[48:49]
	s_add_i32 m0, s23, 0x2000
	s_nop 0
	global_load_lds_dwordx4 v164, s[48:49]
	s_barrier
	s_waitcnt lgkmcnt(0)
	s_waitcnt lgkmcnt(0)
	v_mfma_f32_16x16x32_f16 v[118:121], v[212:215], v[146:149], v[118:121]
	v_mfma_f32_16x16x32_f16 v[114:117], v[238:241], v[146:149], v[114:117]
	v_mfma_f32_16x16x32_f16 v[102:105], v[212:215], v[154:157], v[102:105]
	v_mfma_f32_16x16x32_f16 v[98:101], v[238:241], v[154:157], v[98:101]
	v_mfma_f32_16x16x32_f16 v[86:89], v[212:215], v[188:191], v[86:89]
	v_mfma_f32_16x16x32_f16 v[82:85], v[238:241], v[188:191], v[82:85]
	v_mfma_f32_16x16x32_f16 v[70:73], v[212:215], v[196:199], v[70:73]
	v_mfma_f32_16x16x32_f16 v[66:69], v[238:241], v[196:199], v[66:69]
	v_mfma_f32_16x16x32_f16 v[118:121], v[234:237], v[150:153], v[118:121]
	v_mfma_f32_16x16x32_f16 v[114:117], v[242:245], v[150:153], v[114:117]
	v_mfma_f32_16x16x32_f16 v[102:105], v[234:237], v[158:161], v[102:105]
	v_mfma_f32_16x16x32_f16 v[98:101], v[242:245], v[158:161], v[98:101]
	v_mfma_f32_16x16x32_f16 v[86:89], v[234:237], v[192:195], v[86:89]
	v_mfma_f32_16x16x32_f16 v[82:85], v[242:245], v[192:195], v[82:85]
	v_mfma_f32_16x16x32_f16 v[70:73], v[234:237], v[200:203], v[70:73]
	v_mfma_f32_16x16x32_f16 v[66:69], v[242:245], v[200:203], v[66:69]
	s_mov_b32 m0, s28
	v_lshl_add_u64 v[162:163], v[170:171], 0, s[64:65]
	s_barrier
	ds_read_b128 v[146:149], v210 offset:49152
	ds_read_b128 v[150:153], v210 offset:50176
	ds_read_b128 v[154:157], v210 offset:51200
	ds_read_b128 v[158:161], v210 offset:52224
	ds_read_b128 v[188:191], v210 offset:53248
	ds_read_b128 v[192:195], v210 offset:54272
	ds_read_b128 v[196:199], v210 offset:55296
	ds_read_b128 v[200:203], v210 offset:56320
	global_load_lds_dwordx4 v[162:163], off
	v_lshl_add_u64 v[162:163], v[172:173], 0, s[64:65]
	s_mov_b32 m0, s29
	s_nop 0
	global_load_lds_dwordx4 v[162:163], off
	s_barrier
	s_waitcnt lgkmcnt(0)
	s_waitcnt lgkmcnt(0)
	v_mfma_f32_16x16x32_f16 v[62:65], v[122:125], v[146:149], v[62:65]
	v_mfma_f32_16x16x32_f16 v[58:61], v[138:141], v[146:149], v[58:61]
	v_mfma_f32_16x16x32_f16 v[46:49], v[122:125], v[154:157], v[46:49]
	v_mfma_f32_16x16x32_f16 v[42:45], v[138:141], v[154:157], v[42:45]
	v_mfma_f32_16x16x32_f16 v[30:33], v[122:125], v[188:191], v[30:33]
	v_mfma_f32_16x16x32_f16 v[26:29], v[138:141], v[188:191], v[26:29]
	v_mfma_f32_16x16x32_f16 v[14:17], v[122:125], v[196:199], v[14:17]
	v_mfma_f32_16x16x32_f16 v[10:13], v[138:141], v[196:199], v[10:13]
	v_mfma_f32_16x16x32_f16 v[62:65], v[126:129], v[150:153], v[62:65]
	v_mfma_f32_16x16x32_f16 v[58:61], v[142:145], v[150:153], v[58:61]
	v_mfma_f32_16x16x32_f16 v[46:49], v[126:129], v[158:161], v[46:49]
	v_mfma_f32_16x16x32_f16 v[42:45], v[142:145], v[158:161], v[42:45]
	v_mfma_f32_16x16x32_f16 v[30:33], v[126:129], v[192:195], v[30:33]
	v_mfma_f32_16x16x32_f16 v[26:29], v[142:145], v[192:195], v[26:29]
	v_mfma_f32_16x16x32_f16 v[14:17], v[126:129], v[200:203], v[14:17]
	v_mfma_f32_16x16x32_f16 v[10:13], v[142:145], v[200:203], v[10:13]
	s_barrier
	s_add_u32 s48, s48, 0x80080
	s_addc_u32 s49, s49, 0
	s_add_i32 s23, s50, s75
	s_mov_b32 m0, s23
	s_nop 0
	global_load_lds_dwordx4 v178, s[48:49]
	s_add_i32 m0, s23, 0x2000
	s_nop 0
	global_load_lds_dwordx4 v174, s[48:49]
	s_waitcnt vmcnt(6)
	s_barrier
	v_mfma_f32_16x16x32_f16 v[54:57], v[212:215], v[146:149], v[54:57]
	v_mfma_f32_16x16x32_f16 v[50:53], v[238:241], v[146:149], v[50:53]
	v_mfma_f32_16x16x32_f16 v[38:41], v[212:215], v[154:157], v[38:41]
	v_mfma_f32_16x16x32_f16 v[34:37], v[238:241], v[154:157], v[34:37]
	v_mfma_f32_16x16x32_f16 v[22:25], v[212:215], v[188:191], v[22:25]
	v_mfma_f32_16x16x32_f16 v[18:21], v[238:241], v[188:191], v[18:21]
	v_mfma_f32_16x16x32_f16 v[6:9], v[212:215], v[196:199], v[6:9]
	v_mfma_f32_16x16x32_f16 v[2:5], v[238:241], v[196:199], v[2:5]
	v_mfma_f32_16x16x32_f16 v[54:57], v[234:237], v[150:153], v[54:57]
	v_mfma_f32_16x16x32_f16 v[50:53], v[242:245], v[150:153], v[50:53]
	v_mfma_f32_16x16x32_f16 v[38:41], v[234:237], v[158:161], v[38:41]
	v_mfma_f32_16x16x32_f16 v[34:37], v[242:245], v[158:161], v[34:37]
	v_mfma_f32_16x16x32_f16 v[22:25], v[234:237], v[192:195], v[22:25]
	v_mfma_f32_16x16x32_f16 v[18:21], v[242:245], v[192:195], v[18:21]
	v_mfma_f32_16x16x32_f16 v[6:9], v[234:237], v[200:203], v[6:9]
	v_mfma_f32_16x16x32_f16 v[2:5], v[242:245], v[200:203], v[2:5]
	s_add_i32 s22, s22, 2
	s_add_u32 vcc_lo, vcc_lo, 0x100
	s_addc_u32 vcc_hi, vcc_hi, 0
	s_add_u32 s12, s12, 0x100
	s_addc_u32 s13, s13, 0
	s_cmp_gt_u32 s22, 29
	s_barrier
	s_cbranch_scc0 .LBB0_512
	s_lshl_b32 s12, s83, 8
	s_or_b32 s15, s12, s31
	v_add_u32_e32 v122, s15, v206
	v_cndmask_b32_e64 v124, 0, 1, s[44:45]
	v_ashrrev_i32_e32 v123, 31, v122
	v_mov_b32_e32 v196, 0
	v_cmp_ne_u32_e64 s[12:13], 1, v124
	s_andn2_b64 vcc, exec, s[44:45]
	v_mov_b32_e32 v124, 0
	v_mov_b32_e32 v125, 0
	s_cbranch_vccnz .LBB0_515
	v_lshlrev_b64 v[124:125], 2, v[122:123]
	v_lshl_add_u64 v[126:127], s[80:81], 0, v[124:125]
	v_lshl_add_u64 v[124:125], s[58:59], 0, v[124:125]
	global_load_dword v125, v[124:125], off
	s_nop 0
	global_load_dword v124, v[126:127], off

;     __device__ __forceinline__ void prefetch(const Unit& u, int wr, int wc, int lane) const { lnfold_prefetch(vl, stats, gW, bW, u, wr, wc, lane); }
;     __device__ __forceinline__ void prefetch(const Unit& u, int wr, int wc, int lane) const { lnfold_prefetch(vl, stats, gW, bW, u, wr, wc, lane); }
; #define PG8_STAGE(bufoff, gbase, voff) do { _Pragma("unroll") for (int _i = 0; _i < 2; ++_i) \
;         __builtin_amdgcn_global_load_lds((const unsigned*)((const char*)(gbase) + (voff)[_i]), (LAS unsigned*)(lds + (bufoff) + ldsw + _i * 8192), 16, 0, 0); } while (0)
; #define PG8_LDA(dst, b, h) do { _Pragma("unroll") for (int m = 0; m < 4; ++m) _Pragma("unroll") for (int k = 0; k < 2; ++k) dst[m][k] = *(const LAS f16x8*)(lds + PG8_SA(b, h) + aoff + m * 2048 + k * 1024); } while (0)
; #define PG8_LDB(dst, b, h) do { _Pragma("unroll") for (int n = 0; n < 2; ++n) _Pragma("unroll") for (int k = 0; k < 2; ++k) dst[n][k] = *(const LAS f16x8*)(lds + PG8_SB(b, h) + boff + n * 2048 + k * 1024); } while (0)
; #define PG8_BAR __builtin_amdgcn_s_barrier()
; template <class Epi>
; __device__ __forceinline__ void gemm_phase(LAS unsigned char* lds, const Gemm g0, const StaticOrder& S, const Epi& E) {
;     ...
;         const bool has_next = S.next(ui + 1, nxt);
;         const char* nA = has_next ? (const char*)g.A + (size_t)nxt.pm * tstep : cA; const char* nB = has_next ? (const char*)g.Bt + (size_t)nxt.pn * tstep : cB;
;         for (int t = 0; t < nt; t += 2) {
;             const bool last = (t == nt - 2);
;             if (Epi::PREF && last) E.prefetch(cur, wr, wc, lane);
;             const char* a1 = cA + (size_t)(t + 1) * kstep;
;             const char* a2 = last ? nA : cA + (size_t)(t + 2) * kstep; const char* b2 = last ? nB : cB + (size_t)(t + 2) * kstep;
;             const char* a3 = a2 + kstep; const char* b3 = b2 + kstep;
;             PG8_LDB(B0, 0, 0); PG8_SCHED; PG8_LDA(At, 0, 0); PG8_STAGE(PG8_SA(1, 1), a1 + hstep, voffA);
;             PG8_WAIT_L(8); PG8_BAR; PG8_WAIT_L(0); PG8_MMA(0, 0, At, B0); PG8_BAR; PG8_SCHED;
;     ...
; #pragma unroll
;         for (int a = 0; a < 2; ++a)
; #pragma unroll
;             for (int b = 0; b < 2; ++b)
; #pragma unroll
;                 for (int m = 0; m < 4; ++m)
; #pragma unroll
;                     for (int n = 0; n < 2; ++n) acc[a][b][m][n] = (f32x4){0.f, 0.f, 0.f, 0.f};
;         cur = nxt; cA = nA; cB = nB; ++ui;
.LBB0_619:
	s_ashr_i32 s37, s36, 31
	s_lshl_b64 s[24:25], s[36:37], 20
	v_cmp_lt_i64_e32 vcc, s[38:39], v[230:231]
	s_add_u32 s38, s8, s24
	s_addc_u32 s39, s9, s25
	s_and_b64 s[24:25], vcc, exec
	s_cselect_b32 s37, s39, s53
	s_cselect_b32 s74, s38, s52
	s_ashr_i32 s35, s34, 31
	s_lshl_b64 s[24:25], s[34:35], 20
	s_add_u32 s48, s10, s24
	s_addc_u32 s49, s11, s25
	s_and_b64 s[24:25], vcc, exec
	s_cselect_b32 s35, s49, s51
	s_cselect_b32 s75, s48, s50
	s_lshl_b32 s80, s22, 8
	v_add_u32_e32 v2, s80, v193
	v_lshl_add_u32 v4, s71, 8, v201
	s_add_u32 s24, s50, 0x100
	v_ashrrev_i32_e32 v3, 31, v2
	v_ashrrev_i32_e32 v5, 31, v4
	s_addc_u32 s25, s51, 0
	v_lshlrev_b64 v[4:5], 2, v[4:5]
	v_lshl_add_u64 v[58:59], v[2:3], 3, s[14:15]
	s_add_u32 s50, s52, 0x80080
	v_mov_b32_e32 v2, 0
	v_lshl_add_u64 v[54:55], s[26:27], 0, v[4:5]
	v_lshl_add_u64 v[56:57], s[20:21], 0, v[4:5]
	s_addc_u32 s51, s53, 0
	s_mov_b32 s81, -2
	v_mov_b32_e32 v3, v2
	v_mov_b32_e32 v4, v2
	v_mov_b32_e32 v5, v2
	v_mov_b32_e32 v10, v2
	v_mov_b32_e32 v11, v2
	v_mov_b32_e32 v12, v2
	v_mov_b32_e32 v13, v2
	v_mov_b32_e32 v18, v2
	v_mov_b32_e32 v19, v2
	v_mov_b32_e32 v20, v2
	v_mov_b32_e32 v21, v2
	v_mov_b32_e32 v26, v2
	v_mov_b32_e32 v27, v2
	v_mov_b32_e32 v28, v2
	v_mov_b32_e32 v29, v2
	v_mov_b32_e32 v34, v2
	v_mov_b32_e32 v35, v2
	v_mov_b32_e32 v36, v2
	v_mov_b32_e32 v37, v2
	v_mov_b32_e32 v42, v2
	v_mov_b32_e32 v43, v2
	v_mov_b32_e32 v44, v2
	v_mov_b32_e32 v45, v2
	v_mov_b32_e32 v50, v2
	v_mov_b32_e32 v51, v2
	v_mov_b32_e32 v52, v2
	v_mov_b32_e32 v53, v2
	v_mov_b32_e32 v74, v2
	v_mov_b32_e32 v75, v2
	v_mov_b32_e32 v76, v2
	v_mov_b32_e32 v77, v2
	v_mov_b32_e32 v6, v2
	v_mov_b32_e32 v7, v2
	v_mov_b32_e32 v8, v2
	v_mov_b32_e32 v9, v2
	v_mov_b32_e32 v14, v2
	v_mov_b32_e32 v15, v2
	v_mov_b32_e32 v16, v2
	v_mov_b32_e32 v17, v2
	v_mov_b32_e32 v22, v2
	v_mov_b32_e32 v23, v2
	v_mov_b32_e32 v24, v2
	v_mov_b32_e32 v25, v2
	v_mov_b32_e32 v30, v2
	v_mov_b32_e32 v31, v2
	v_mov_b32_e32 v32, v2
	v_mov_b32_e32 v33, v2
	v_mov_b32_e32 v38, v2
	v_mov_b32_e32 v39, v2
	v_mov_b32_e32 v40, v2
	v_mov_b32_e32 v41, v2
	v_mov_b32_e32 v46, v2
	v_mov_b32_e32 v47, v2
	v_mov_b32_e32 v48, v2
	v_mov_b32_e32 v49, v2
	v_mov_b32_e32 v70, v2
	v_mov_b32_e32 v71, v2
	v_mov_b32_e32 v72, v2
	v_mov_b32_e32 v73, v2
	v_mov_b32_e32 v94, v2
	v_mov_b32_e32 v95, v2
	v_mov_b32_e32 v96, v2
	v_mov_b32_e32 v97, v2
	v_mov_b32_e32 v98, v2
	v_mov_b32_e32 v99, v2
	v_mov_b32_e32 v100, v2
	v_mov_b32_e32 v101, v2
	v_mov_b32_e32 v106, v2
	v_mov_b32_e32 v107, v2
	v_mov_b32_e32 v108, v2
	v_mov_b32_e32 v109, v2
	v_mov_b32_e32 v114, v2
	v_mov_b32_e32 v115, v2
	v_mov_b32_e32 v116, v2
	v_mov_b32_e32 v117, v2
	v_mov_b32_e32 v122, v2
	v_mov_b32_e32 v123, v2
	v_mov_b32_e32 v124, v2
	v_mov_b32_e32 v125, v2
	v_mov_b32_e32 v130, v2
	v_mov_b32_e32 v131, v2
	v_mov_b32_e32 v132, v2
	v_mov_b32_e32 v133, v2
	v_mov_b32_e32 v138, v2
	v_mov_b32_e32 v139, v2
	v_mov_b32_e32 v140, v2
	v_mov_b32_e32 v141, v2
	v_mov_b32_e32 v146, v2
	v_mov_b32_e32 v147, v2
	v_mov_b32_e32 v148, v2
	v_mov_b32_e32 v149, v2
	v_mov_b32_e32 v154, v2
	v_mov_b32_e32 v155, v2
	v_mov_b32_e32 v156, v2
	v_mov_b32_e32 v157, v2
	v_mov_b32_e32 v102, v2
	v_mov_b32_e32 v103, v2
	v_mov_b32_e32 v104, v2
	v_mov_b32_e32 v105, v2
	v_mov_b32_e32 v110, v2
	v_mov_b32_e32 v111, v2
	v_mov_b32_e32 v112, v2
	v_mov_b32_e32 v113, v2
	v_mov_b32_e32 v118, v2
	v_mov_b32_e32 v119, v2
	v_mov_b32_e32 v120, v2
	v_mov_b32_e32 v121, v2
	v_mov_b32_e32 v126, v2
	v_mov_b32_e32 v127, v2
	v_mov_b32_e32 v128, v2
	v_mov_b32_e32 v129, v2
	v_mov_b32_e32 v134, v2
	v_mov_b32_e32 v135, v2
	v_mov_b32_e32 v136, v2
	v_mov_b32_e32 v137, v2
	v_mov_b32_e32 v142, v2
	v_mov_b32_e32 v143, v2
	v_mov_b32_e32 v144, v2
	v_mov_b32_e32 v145, v2
	v_mov_b32_e32 v150, v2
	v_mov_b32_e32 v151, v2
	v_mov_b32_e32 v152, v2
	v_mov_b32_e32 v153, v2
	v_mov_b32_e32 v158, v2
	v_mov_b32_e32 v159, v2
	v_mov_b32_e32 v160, v2
	v_mov_b32_e32 v161, v2
	v_add_u32_e32 v186, 0x80, v178
	v_add_u32_e32 v190, 0x80, v174
	v_add_u32_e32 v198, 0x80, v180
	v_add_u32_e32 v202, 0x80, v176
	v_add_u32_e32 v187, 0x10000, v189
	s_branch .LBB0_621
.LBB0_620:
	s_add_u32 s58, s50, 0xfff80080
	s_addc_u32 s59, s51, -1
	s_and_b64 s[22:23], s[52:53], exec
	s_cselect_b32 s59, s37, s59
	s_cselect_b32 s58, s74, s58
	s_add_i32 s82, 0, 0x10000
	ds_read_b128 v[60:63], v187
	ds_read_b128 v[64:67], v187 offset:1024
	ds_read_b128 v[78:81], v187 offset:2048
	ds_read_b128 v[82:85], v187 offset:3072
	s_and_b64 s[22:23], s[52:53], exec
	s_cselect_b32 s53, s35, s25
	s_cselect_b32 s52, s75, s24
	s_add_i32 m0, s18, 0xc000
	ds_read_b128 v[86:89], v213
	ds_read_b128 v[90:93], v213 offset:1024
	ds_read_b128 v[194:197], v213 offset:2048
	ds_read_b128 v[234:237], v213 offset:3072
	ds_read_b128 v[238:241], v213 offset:4096
	ds_read_b128 v[242:245], v213 offset:5120
	ds_read_b128 v[246:249], v213 offset:6144
	ds_read_b128 v[226:229], v213 offset:7168
	global_load_lds_dwordx4 v184, s[50:51]
	s_add_i32 m0, s18, 0xe000
	s_nop 0
	global_load_lds_dwordx4 v182, s[50:51]
	s_waitcnt lgkmcnt(8)
	s_barrier
	s_waitcnt lgkmcnt(0)
	s_waitcnt lgkmcnt(0)
	v_mfma_f32_16x16x32_f16 v[158:161], v[60:63], v[86:89], v[158:161]
	v_mfma_f32_16x16x32_f16 v[150:153], v[78:81], v[86:89], v[150:153]
	v_mfma_f32_16x16x32_f16 v[142:145], v[60:63], v[194:197], v[142:145]
	v_mfma_f32_16x16x32_f16 v[134:137], v[78:81], v[194:197], v[134:137]
	v_mfma_f32_16x16x32_f16 v[126:129], v[60:63], v[238:241], v[126:129]
	v_mfma_f32_16x16x32_f16 v[118:121], v[78:81], v[238:241], v[118:121]
	v_mfma_f32_16x16x32_f16 v[110:113], v[60:63], v[246:249], v[110:113]
	v_mfma_f32_16x16x32_f16 v[102:105], v[78:81], v[246:249], v[102:105]
	v_mfma_f32_16x16x32_f16 v[158:161], v[64:67], v[90:93], v[158:161]
	v_mfma_f32_16x16x32_f16 v[150:153], v[82:85], v[90:93], v[150:153]
	v_mfma_f32_16x16x32_f16 v[142:145], v[64:67], v[234:237], v[142:145]
	v_mfma_f32_16x16x32_f16 v[134:137], v[82:85], v[234:237], v[134:137]
	v_mfma_f32_16x16x32_f16 v[126:129], v[64:67], v[242:245], v[126:129]
	v_mfma_f32_16x16x32_f16 v[118:121], v[82:85], v[242:245], v[118:121]
	v_mfma_f32_16x16x32_f16 v[110:113], v[64:67], v[226:229], v[110:113]
	v_mfma_f32_16x16x32_f16 v[102:105], v[82:85], v[226:229], v[102:105]
	s_barrier
; #define PG8_STAGE(bufoff, gbase, voff) do { _Pragma("unroll") for (int _i = 0; _i < 2; ++_i) \
;         __builtin_amdgcn_global_load_lds((const unsigned*)((const char*)(gbase) + (voff)[_i]), (LAS unsigned*)(lds + (bufoff) + ldsw + _i * 8192), 16, 0, 0); } while (0)
; #define PG8_LDA(dst, b, h) do { _Pragma("unroll") for (int m = 0; m < 4; ++m) _Pragma("unroll") for (int k = 0; k < 2; ++k) dst[m][k] = *(const LAS f16x8*)(lds + PG8_SA(b, h) + aoff + m * 2048 + k * 1024); } while (0)
; #define PG8_LDB(dst, b, h) do { _Pragma("unroll") for (int n = 0; n < 2; ++n) _Pragma("unroll") for (int k = 0; k < 2; ++k) dst[n][k] = *(const LAS f16x8*)(lds + PG8_SB(b, h) + boff + n * 2048 + k * 1024); } while (0)
; #define PG8_MMA(ai, bj, At, Bt) do { __builtin_amdgcn_s_setprio(1); _Pragma("unroll") for (int m = 0; m < 4; ++m) _Pragma("unroll") for (int n = 0; n < 2; ++n) _Pragma("unroll") for (int k = 0; k < 2; ++k) \
;         acc[ai][bj][m][n] = __builtin_amdgcn_mfma_f32_16x16x32_f16(Bt[n][k], At[m][k], acc[ai][bj][m][n], 0, 0, 0); __builtin_amdgcn_s_setprio(0); } while (0)
; #define PG8_WAIT_V(n) asm volatile("s_waitcnt vmcnt(" #n ")" ::: "memory")
; #define PG8_WAIT_L(n) asm volatile("s_waitcnt lgkmcnt(" #n ")" ::: "memory")
; #define PG8_BAR __builtin_amdgcn_s_barrier()
; #define PG8_SCHED __builtin_amdgcn_sched_barrier(0)
; template <class Epi>
; __device__ __forceinline__ void gemm_phase(LAS unsigned char* lds, const Gemm g0, const StaticOrder& S, const Epi& E) {
;     ...
;             PG8_LDB(B1, 0, 1); PG8_STAGE(PG8_SB(0, 0), b2, voffB);
;             PG8_BAR; PG8_WAIT_L(0); PG8_MMA(0, 1, At, B1); PG8_BAR;
;             PG8_LDA(At, 0, 1); PG8_STAGE(PG8_SA(0, 0), a2, voffA);
;             PG8_BAR; PG8_WAIT_L(0); PG8_MMA(1, 0, At, B0); PG8_BAR; PG8_SCHED;
;             PG8_STAGE(PG8_SB(0, 1), b2 + hstep, voffB);
;             PG8_WAIT_V(6); PG8_BAR; PG8_MMA(1, 1, At, B1); PG8_BAR;
;             PG8_LDB(B0, 1, 0); PG8_SCHED; PG8_LDA(At, 1, 0); PG8_STAGE(PG8_SA(0, 1), a2 + hstep, voffA);
;             PG8_WAIT_L(8); PG8_BAR; PG8_WAIT_L(0); PG8_MMA(0, 0, At, B0); PG8_BAR; PG8_SCHED;
	s_add_i32 s83, 0, 0x14000
	s_add_i32 s22, s82, s5
	s_mov_b32 m0, s22
	ds_read_b128 v[162:165], v187 offset:16384
	ds_read_b128 v[222:225], v187 offset:17408
	ds_read_b128 v[214:217], v187 offset:18432
	ds_read_b128 v[170:173], v187 offset:19456
	global_load_lds_dwordx4 v178, s[52:53]
	s_add_i32 m0, s22, 0x2000
	s_nop 0
	global_load_lds_dwordx4 v174, s[52:53]
	s_barrier
	s_waitcnt lgkmcnt(0)
	s_waitcnt lgkmcnt(0)
	v_mfma_f32_16x16x32_f16 v[154:157], v[162:165], v[86:89], v[154:157]
	v_mfma_f32_16x16x32_f16 v[86:89], v[214:217], v[86:89], v[146:149]
	v_mfma_f32_16x16x32_f16 v[130:133], v[214:217], v[194:197], v[130:133]
	v_mfma_f32_16x16x32_f16 v[122:125], v[162:165], v[238:241], v[122:125]
	v_mfma_f32_16x16x32_f16 v[114:117], v[214:217], v[238:241], v[114:117]
	v_mfma_f32_16x16x32_f16 v[106:109], v[162:165], v[246:249], v[106:109]
	v_mfma_f32_16x16x32_f16 v[98:101], v[214:217], v[246:249], v[98:101]
	v_mfma_f32_16x16x32_f16 v[154:157], v[222:225], v[90:93], v[154:157]
	v_mfma_f32_16x16x32_f16 v[86:89], v[170:173], v[90:93], v[86:89]
	v_mfma_f32_16x16x32_f16 v[90:93], v[162:165], v[194:197], v[138:141]
	v_mfma_f32_16x16x32_f16 v[130:133], v[170:173], v[234:237], v[130:133]
	v_mfma_f32_16x16x32_f16 v[122:125], v[222:225], v[242:245], v[122:125]
	v_mfma_f32_16x16x32_f16 v[114:117], v[170:173], v[242:245], v[114:117]
	v_mfma_f32_16x16x32_f16 v[106:109], v[222:225], v[226:229], v[106:109]
	v_mfma_f32_16x16x32_f16 v[98:101], v[170:173], v[226:229], v[98:101]
	v_mfma_f32_16x16x32_f16 v[90:93], v[222:225], v[234:237], v[90:93]
	s_mov_b32 m0, s18
	s_barrier
	ds_read_b128 v[138:141], v213 offset:16384
	ds_read_b128 v[146:149], v213 offset:17408
	ds_read_b128 v[194:197], v213 offset:18432
	ds_read_b128 v[226:229], v213 offset:19456
	ds_read_b128 v[234:237], v213 offset:20480
	ds_read_b128 v[238:241], v213 offset:21504
	ds_read_b128 v[242:245], v213 offset:22528
	ds_read_b128 v[246:249], v213 offset:23552
	global_load_lds_dwordx4 v180, s[58:59]
	s_mov_b32 m0, s19
	s_nop 0
	global_load_lds_dwordx4 v176, s[58:59]
	s_barrier
	s_waitcnt lgkmcnt(0)
	s_waitcnt lgkmcnt(0)
	v_mfma_f32_16x16x32_f16 v[94:97], v[60:63], v[138:141], v[94:97]
	v_mfma_f32_16x16x32_f16 v[68:71], v[78:81], v[138:141], v[70:73]
	v_mfma_f32_16x16x32_f16 v[46:49], v[60:63], v[194:197], v[46:49]
	v_mfma_f32_16x16x32_f16 v[38:41], v[78:81], v[194:197], v[38:41]
	v_mfma_f32_16x16x32_f16 v[30:33], v[60:63], v[234:237], v[30:33]
	v_mfma_f32_16x16x32_f16 v[22:25], v[78:81], v[234:237], v[22:25]
	v_mfma_f32_16x16x32_f16 v[14:17], v[60:63], v[242:245], v[14:17]
	v_mfma_f32_16x16x32_f16 v[6:9], v[78:81], v[242:245], v[6:9]
	v_mfma_f32_16x16x32_f16 v[94:97], v[64:67], v[146:149], v[94:97]
	v_mfma_f32_16x16x32_f16 v[68:71], v[82:85], v[146:149], v[68:71]
	v_mfma_f32_16x16x32_f16 v[46:49], v[64:67], v[226:229], v[46:49]
	v_mfma_f32_16x16x32_f16 v[38:41], v[82:85], v[226:229], v[38:41]
	v_mfma_f32_16x16x32_f16 v[30:33], v[64:67], v[238:241], v[30:33]
	v_mfma_f32_16x16x32_f16 v[22:25], v[82:85], v[238:241], v[22:25]
	v_mfma_f32_16x16x32_f16 v[14:17], v[64:67], v[246:249], v[14:17]
	v_mfma_f32_16x16x32_f16 v[6:9], v[82:85], v[246:249], v[6:9]
	s_barrier
	s_add_u32 s22, s52, 0x80000
	s_addc_u32 s23, s53, 0
	s_add_i32 s82, s83, s5
	s_mov_b32 m0, s82
	s_nop 0
	global_load_lds_dwordx4 v178, s[22:23]
	s_add_i32 m0, s82, 0x2000
	s_nop 0
	global_load_lds_dwordx4 v174, s[22:23]
	s_waitcnt vmcnt(6)
	s_barrier
	v_mfma_f32_16x16x32_f16 v[50:53], v[214:217], v[138:141], v[50:53]
	v_mfma_f32_16x16x32_f16 v[42:45], v[162:165], v[194:197], v[42:45]
	v_mfma_f32_16x16x32_f16 v[34:37], v[214:217], v[194:197], v[34:37]
	v_mfma_f32_16x16x32_f16 v[26:29], v[162:165], v[234:237], v[26:29]
	v_mfma_f32_16x16x32_f16 v[18:21], v[214:217], v[234:237], v[18:21]
	v_mfma_f32_16x16x32_f16 v[10:13], v[162:165], v[242:245], v[10:13]
	v_mfma_f32_16x16x32_f16 v[2:5], v[214:217], v[242:245], v[2:5]
	v_mfma_f32_16x16x32_f16 v[60:63], v[162:165], v[138:141], v[74:77]
	v_mfma_f32_16x16x32_f16 v[50:53], v[170:173], v[146:149], v[50:53]
	v_mfma_f32_16x16x32_f16 v[42:45], v[222:225], v[226:229], v[42:45]
	v_mfma_f32_16x16x32_f16 v[34:37], v[170:173], v[226:229], v[34:37]
	v_mfma_f32_16x16x32_f16 v[26:29], v[222:225], v[238:241], v[26:29]
	v_mfma_f32_16x16x32_f16 v[18:21], v[170:173], v[238:241], v[18:21]
	v_mfma_f32_16x16x32_f16 v[10:13], v[222:225], v[246:249], v[10:13]
	v_mfma_f32_16x16x32_f16 v[2:5], v[170:173], v[246:249], v[2:5]
	v_mfma_f32_16x16x32_f16 v[60:63], v[222:225], v[146:149], v[60:63]
	s_add_i32 s82, 0, 0x18000
	s_barrier
	ds_read_b128 v[64:67], v187 offset:32768
	ds_read_b128 v[74:77], v187 offset:33792
	ds_read_b128 v[78:81], v187 offset:34816
	ds_read_b128 v[82:85], v187 offset:35840
	s_add_u32 s22, s58, 0x80000
	s_addc_u32 s23, s59, 0
	s_mov_b32 m0, s28
	ds_read_b128 v[138:141], v213 offset:32768
	ds_read_b128 v[146:149], v213 offset:33792
	ds_read_b128 v[162:165], v213 offset:34816
	ds_read_b128 v[170:173], v213 offset:35840
	ds_read_b128 v[194:197], v213 offset:36864
	ds_read_b128 v[214:217], v213 offset:37888
	ds_read_b128 v[222:225], v213 offset:38912
	ds_read_b128 v[226:229], v213 offset:39936
	global_load_lds_dwordx4 v180, s[22:23]
	s_mov_b32 m0, s29
	s_nop 0
	global_load_lds_dwordx4 v176, s[22:23]
	s_waitcnt lgkmcnt(8)
	s_barrier
; #define PG8_STAGE(bufoff, gbase, voff) do { _Pragma("unroll") for (int _i = 0; _i < 2; ++_i) \
;         __builtin_amdgcn_global_load_lds((const unsigned*)((const char*)(gbase) + (voff)[_i]), (LAS unsigned*)(lds + (bufoff) + ldsw + _i * 8192), 16, 0, 0); } while (0)
; #define PG8_LDA(dst, b, h) do { _Pragma("unroll") for (int m = 0; m < 4; ++m) _Pragma("unroll") for (int k = 0; k < 2; ++k) dst[m][k] = *(const LAS f16x8*)(lds + PG8_SA(b, h) + aoff + m * 2048 + k * 1024); } while (0)
; #define PG8_LDB(dst, b, h) do { _Pragma("unroll") for (int n = 0; n < 2; ++n) _Pragma("unroll") for (int k = 0; k < 2; ++k) dst[n][k] = *(const LAS f16x8*)(lds + PG8_SB(b, h) + boff + n * 2048 + k * 1024); } while (0)
; #define PG8_MMA(ai, bj, At, Bt) do { __builtin_amdgcn_s_setprio(1); _Pragma("unroll") for (int m = 0; m < 4; ++m) _Pragma("unroll") for (int n = 0; n < 2; ++n) _Pragma("unroll") for (int k = 0; k < 2; ++k) \
;         acc[ai][bj][m][n] = __builtin_amdgcn_mfma_f32_16x16x32_f16(Bt[n][k], At[m][k], acc[ai][bj][m][n], 0, 0, 0); __builtin_amdgcn_s_setprio(0); } while (0)
; #define PG8_WAIT_V(n) asm volatile("s_waitcnt vmcnt(" #n ")" ::: "memory")
; #define PG8_WAIT_L(n) asm volatile("s_waitcnt lgkmcnt(" #n ")" ::: "memory")
; #define PG8_BAR __builtin_amdgcn_s_barrier()
; #define PG8_SCHED __builtin_amdgcn_sched_barrier(0)
; template <class Epi>
; __device__ __forceinline__ void gemm_phase(LAS unsigned char* lds, const Gemm g0, const StaticOrder& S, const Epi& E) {
;     ...
;             PG8_WAIT_L(8); PG8_BAR; PG8_WAIT_L(0); PG8_MMA(0, 0, At, B0); PG8_BAR; PG8_SCHED;
;             PG8_LDB(B1, 1, 1); PG8_STAGE(PG8_SB(1, 0), b3, voffB);
;             PG8_BAR; PG8_WAIT_L(0); PG8_MMA(0, 1, At, B1); PG8_BAR;
;             PG8_LDA(At, 1, 1); PG8_STAGE(PG8_SA(1, 0), a3, voffA);
;             PG8_BAR; PG8_WAIT_L(0); PG8_MMA(1, 0, At, B0); PG8_BAR; PG8_SCHED;
;             PG8_STAGE(PG8_SB(1, 1), b3 + hstep, voffB);
;             PG8_WAIT_V(6); PG8_BAR; PG8_MMA(1, 1, At, B1); PG8_BAR;
;         }
	s_waitcnt lgkmcnt(0)
	s_waitcnt lgkmcnt(0)
	v_mfma_f32_16x16x32_f16 v[158:161], v[64:67], v[138:141], v[158:161]
	v_mfma_f32_16x16x32_f16 v[150:153], v[78:81], v[138:141], v[150:153]
	v_mfma_f32_16x16x32_f16 v[142:145], v[64:67], v[162:165], v[142:145]
	v_mfma_f32_16x16x32_f16 v[134:137], v[78:81], v[162:165], v[134:137]
	v_mfma_f32_16x16x32_f16 v[126:129], v[64:67], v[194:197], v[126:129]
	v_mfma_f32_16x16x32_f16 v[118:121], v[78:81], v[194:197], v[118:121]
	v_mfma_f32_16x16x32_f16 v[110:113], v[64:67], v[222:225], v[110:113]
	v_mfma_f32_16x16x32_f16 v[102:105], v[78:81], v[222:225], v[102:105]
	v_mfma_f32_16x16x32_f16 v[158:161], v[74:77], v[146:149], v[158:161]
	v_mfma_f32_16x16x32_f16 v[150:153], v[82:85], v[146:149], v[150:153]
	v_mfma_f32_16x16x32_f16 v[142:145], v[74:77], v[170:173], v[142:145]
	v_mfma_f32_16x16x32_f16 v[134:137], v[82:85], v[170:173], v[134:137]
	v_mfma_f32_16x16x32_f16 v[126:129], v[74:77], v[214:217], v[126:129]
	v_mfma_f32_16x16x32_f16 v[118:121], v[82:85], v[214:217], v[118:121]
	v_mfma_f32_16x16x32_f16 v[110:113], v[74:77], v[226:229], v[110:113]
	v_mfma_f32_16x16x32_f16 v[102:105], v[82:85], v[226:229], v[102:105]
	s_barrier
	s_add_i32 s83, 0, 0x1c000
	s_add_i32 s22, s82, s5
	ds_read_b128 v[234:237], v187 offset:49152
	ds_read_b128 v[238:241], v187 offset:50176
	ds_read_b128 v[242:245], v187 offset:51200
	ds_read_b128 v[246:249], v187 offset:52224
	s_mov_b32 m0, s22
	s_nop 0
	global_load_lds_dwordx4 v186, s[52:53]
	s_add_i32 m0, s22, 0x2000
	s_nop 0
	global_load_lds_dwordx4 v190, s[52:53]
	s_barrier
	s_waitcnt lgkmcnt(0)
	s_waitcnt lgkmcnt(0)
	v_mfma_f32_16x16x32_f16 v[154:157], v[234:237], v[138:141], v[154:157]
	v_mfma_f32_16x16x32_f16 v[86:89], v[242:245], v[138:141], v[86:89]
	v_mfma_f32_16x16x32_f16 v[154:157], v[238:241], v[146:149], v[154:157]
	v_mfma_f32_16x16x32_f16 v[146:149], v[246:249], v[146:149], v[86:89]
	v_mfma_f32_16x16x32_f16 v[86:89], v[234:237], v[162:165], v[90:93]
	v_mfma_f32_16x16x32_f16 v[138:141], v[238:241], v[170:173], v[86:89]
	v_mfma_f32_16x16x32_f16 v[86:89], v[242:245], v[162:165], v[130:133]
	v_mfma_f32_16x16x32_f16 v[130:133], v[246:249], v[170:173], v[86:89]
	v_mfma_f32_16x16x32_f16 v[86:89], v[234:237], v[194:197], v[122:125]
	v_mfma_f32_16x16x32_f16 v[122:125], v[238:241], v[214:217], v[86:89]
	v_mfma_f32_16x16x32_f16 v[86:89], v[242:245], v[194:197], v[114:117]
	v_mfma_f32_16x16x32_f16 v[114:117], v[246:249], v[214:217], v[86:89]
	v_mfma_f32_16x16x32_f16 v[86:89], v[234:237], v[222:225], v[106:109]
	v_mfma_f32_16x16x32_f16 v[106:109], v[238:241], v[226:229], v[86:89]
	v_mfma_f32_16x16x32_f16 v[86:89], v[242:245], v[222:225], v[98:101]
	v_mfma_f32_16x16x32_f16 v[98:101], v[246:249], v[226:229], v[86:89]
	s_mov_b32 m0, s31
	s_barrier
	s_nop 2
	ds_read_b128 v[86:89], v213 offset:49152
	ds_read_b128 v[90:93], v213 offset:50176
	ds_read_b128 v[162:165], v213 offset:51200
	ds_read_b128 v[170:173], v213 offset:52224
	ds_read_b128 v[194:197], v213 offset:53248
	ds_read_b128 v[214:217], v213 offset:54272
	ds_read_b128 v[222:225], v213 offset:55296
	ds_read_b128 v[226:229], v213 offset:56320
	global_load_lds_dwordx4 v198, s[58:59]
	s_mov_b32 m0, s61
	s_nop 0
	global_load_lds_dwordx4 v202, s[58:59]
	s_barrier
	s_waitcnt lgkmcnt(0)
	s_waitcnt lgkmcnt(0)
	v_mfma_f32_16x16x32_f16 v[94:97], v[64:67], v[86:89], v[94:97]
	v_mfma_f32_16x16x32_f16 v[68:71], v[78:81], v[86:89], v[68:71]
	v_mfma_f32_16x16x32_f16 v[46:49], v[64:67], v[162:165], v[46:49]
	v_mfma_f32_16x16x32_f16 v[38:41], v[78:81], v[162:165], v[38:41]
	v_mfma_f32_16x16x32_f16 v[30:33], v[64:67], v[194:197], v[30:33]
	v_mfma_f32_16x16x32_f16 v[22:25], v[78:81], v[194:197], v[22:25]
	v_mfma_f32_16x16x32_f16 v[14:17], v[64:67], v[222:225], v[14:17]
	v_mfma_f32_16x16x32_f16 v[6:9], v[78:81], v[222:225], v[6:9]
	v_mfma_f32_16x16x32_f16 v[94:97], v[74:77], v[90:93], v[94:97]
	v_mfma_f32_16x16x32_f16 v[70:73], v[82:85], v[90:93], v[68:71]
	v_mfma_f32_16x16x32_f16 v[46:49], v[74:77], v[170:173], v[46:49]
	v_mfma_f32_16x16x32_f16 v[38:41], v[82:85], v[170:173], v[38:41]
	v_mfma_f32_16x16x32_f16 v[30:33], v[74:77], v[214:217], v[30:33]
	v_mfma_f32_16x16x32_f16 v[22:25], v[82:85], v[214:217], v[22:25]
	v_mfma_f32_16x16x32_f16 v[14:17], v[74:77], v[226:229], v[14:17]
	v_mfma_f32_16x16x32_f16 v[6:9], v[82:85], v[226:229], v[6:9]
	s_barrier
	s_add_u32 s22, s52, 0x80080
	s_addc_u32 s23, s53, 0
	s_add_i32 s52, s83, s5
	s_mov_b32 m0, s52
	s_nop 0
	global_load_lds_dwordx4 v178, s[22:23]
	s_add_i32 m0, s52, 0x2000
	s_nop 0
	global_load_lds_dwordx4 v174, s[22:23]
	s_waitcnt vmcnt(6)
	s_barrier
	v_mfma_f32_16x16x32_f16 v[60:63], v[234:237], v[86:89], v[60:63]
	v_mfma_f32_16x16x32_f16 v[50:53], v[242:245], v[86:89], v[50:53]
	v_mfma_f32_16x16x32_f16 v[42:45], v[234:237], v[162:165], v[42:45]
	v_mfma_f32_16x16x32_f16 v[34:37], v[242:245], v[162:165], v[34:37]
	v_mfma_f32_16x16x32_f16 v[26:29], v[234:237], v[194:197], v[26:29]
	v_mfma_f32_16x16x32_f16 v[18:21], v[242:245], v[194:197], v[18:21]
	v_mfma_f32_16x16x32_f16 v[10:13], v[234:237], v[222:225], v[10:13]
	v_mfma_f32_16x16x32_f16 v[2:5], v[242:245], v[222:225], v[2:5]
	v_mfma_f32_16x16x32_f16 v[74:77], v[238:241], v[90:93], v[60:63]
	v_mfma_f32_16x16x32_f16 v[50:53], v[246:249], v[90:93], v[50:53]
	v_mfma_f32_16x16x32_f16 v[42:45], v[238:241], v[170:173], v[42:45]
	v_mfma_f32_16x16x32_f16 v[34:37], v[246:249], v[170:173], v[34:37]
	v_mfma_f32_16x16x32_f16 v[26:29], v[238:241], v[214:217], v[26:29]
	v_mfma_f32_16x16x32_f16 v[18:21], v[246:249], v[214:217], v[18:21]
	v_mfma_f32_16x16x32_f16 v[10:13], v[238:241], v[226:229], v[10:13]
	v_mfma_f32_16x16x32_f16 v[2:5], v[246:249], v[226:229], v[2:5]
	s_add_i32 s81, s81, 2
	s_add_u32 s24, s24, 0x100
	s_addc_u32 s25, s25, 0
	s_add_u32 s50, s50, 0x100
	s_addc_u32 s51, s51, 0
	s_cmp_gt_u32 s81, 29
	s_barrier
	s_cbranch_scc1 .LBB0_616

;     __device__ __forceinline__ void prefetch(const Unit& u, int wr, int wc, int lane) const { lnfold_prefetch(vl, stats, gW, bW, u, wr, wc, lane); }
;     __device__ __forceinline__ void prefetch(const Unit& u, int wr, int wc, int lane) const { lnfold_prefetch(vl, stats, gW, bW, u, wr, wc, lane); }
; #define PG8_STAGE(bufoff, gbase, voff) do { _Pragma("unroll") for (int _i = 0; _i < 2; ++_i) \
;         __builtin_amdgcn_global_load_lds((const unsigned*)((const char*)(gbase) + (voff)[_i]), (LAS unsigned*)(lds + (bufoff) + ldsw + _i * 8192), 16, 0, 0); } while (0)
; #define PG8_LDA(dst, b, h) do { _Pragma("unroll") for (int m = 0; m < 4; ++m) _Pragma("unroll") for (int k = 0; k < 2; ++k) dst[m][k] = *(const LAS f16x8*)(lds + PG8_SA(b, h) + aoff + m * 2048 + k * 1024); } while (0)
; #define PG8_LDB(dst, b, h) do { _Pragma("unroll") for (int n = 0; n < 2; ++n) _Pragma("unroll") for (int k = 0; k < 2; ++k) dst[n][k] = *(const LAS f16x8*)(lds + PG8_SB(b, h) + boff + n * 2048 + k * 1024); } while (0)
; #define PG8_BAR __builtin_amdgcn_s_barrier()
; template <class Epi>
; __device__ __forceinline__ void gemm_phase(LAS unsigned char* lds, const Gemm g0, const StaticOrder& S, const Epi& E) {
;     ...
;         const bool has_next = S.next(ui + 1, nxt);
;         const char* nA = has_next ? (const char*)g.A + (size_t)nxt.pm * tstep : cA; const char* nB = has_next ? (const char*)g.Bt + (size_t)nxt.pn * tstep : cB;
;         for (int t = 0; t < nt; t += 2) {
;             const bool last = (t == nt - 2);
;             if (Epi::PREF && last) E.prefetch(cur, wr, wc, lane);
;             const char* a1 = cA + (size_t)(t + 1) * kstep;
;             const char* a2 = last ? nA : cA + (size_t)(t + 2) * kstep; const char* b2 = last ? nB : cB + (size_t)(t + 2) * kstep;
;             const char* a3 = a2 + kstep; const char* b3 = b2 + kstep;
;             PG8_LDB(B0, 0, 0); PG8_SCHED; PG8_LDA(At, 0, 0); PG8_STAGE(PG8_SA(1, 1), a1 + hstep, voffA);
;             PG8_WAIT_L(8); PG8_BAR; PG8_WAIT_L(0); PG8_MMA(0, 0, At, B0); PG8_BAR; PG8_SCHED;
;     ...
; #pragma unroll
;         for (int a = 0; a < 2; ++a)
; #pragma unroll
;             for (int b = 0; b < 2; ++b)
; #pragma unroll
;                 for (int m = 0; m < 4; ++m)
; #pragma unroll
;                     for (int n = 0; n < 2; ++n) acc[a][b][m][n] = (f32x4){0.f, 0.f, 0.f, 0.f};
;         cur = nxt; cA = nA; cB = nB; ++ui;
.LBB0_671:
	s_add_u32 s24, s62, 0x100
	v_mov_b32_e32 v2, 0
	s_addc_u32 s25, s63, 0
	s_mov_b32 s22, -2
	s_waitcnt lgkmcnt(0)
	v_mov_b32_e32 v3, v2
	v_mov_b32_e32 v4, v2
	v_mov_b32_e32 v5, v2
	v_mov_b32_e32 v6, v2
	v_mov_b32_e32 v7, v2
	v_mov_b32_e32 v8, v2
	v_mov_b32_e32 v9, v2
	v_mov_b32_e32 v18, v2
	v_mov_b32_e32 v19, v2
	v_mov_b32_e32 v20, v2
	v_mov_b32_e32 v21, v2
	v_mov_b32_e32 v22, v2
	v_mov_b32_e32 v23, v2
	v_mov_b32_e32 v24, v2
	v_mov_b32_e32 v25, v2
	v_mov_b32_e32 v34, v2
	v_mov_b32_e32 v35, v2
	v_mov_b32_e32 v36, v2
	v_mov_b32_e32 v37, v2
	v_mov_b32_e32 v38, v2
	v_mov_b32_e32 v39, v2
	v_mov_b32_e32 v40, v2
	v_mov_b32_e32 v41, v2
	v_mov_b32_e32 v50, v2
	v_mov_b32_e32 v51, v2
	v_mov_b32_e32 v52, v2
	v_mov_b32_e32 v53, v2
	v_mov_b32_e32 v54, v2
	v_mov_b32_e32 v55, v2
	v_mov_b32_e32 v56, v2
	v_mov_b32_e32 v57, v2
	v_mov_b32_e32 v10, v2
	v_mov_b32_e32 v11, v2
	v_mov_b32_e32 v12, v2
	v_mov_b32_e32 v13, v2
	v_mov_b32_e32 v14, v2
	v_mov_b32_e32 v15, v2
	v_mov_b32_e32 v16, v2
	v_mov_b32_e32 v17, v2
	v_mov_b32_e32 v26, v2
	v_mov_b32_e32 v27, v2
	v_mov_b32_e32 v28, v2
	v_mov_b32_e32 v29, v2
	v_mov_b32_e32 v30, v2
	v_mov_b32_e32 v31, v2
	v_mov_b32_e32 v32, v2
	v_mov_b32_e32 v33, v2
	v_mov_b32_e32 v42, v2
	v_mov_b32_e32 v43, v2
	v_mov_b32_e32 v44, v2
	v_mov_b32_e32 v45, v2
	v_mov_b32_e32 v46, v2
	v_mov_b32_e32 v47, v2
	v_mov_b32_e32 v48, v2
	v_mov_b32_e32 v49, v2
	v_mov_b32_e32 v58, v2
	v_mov_b32_e32 v59, v2
	v_mov_b32_e32 v60, v2
	v_mov_b32_e32 v61, v2
	v_mov_b32_e32 v62, v2
	v_mov_b32_e32 v63, v2
	v_mov_b32_e32 v64, v2
	v_mov_b32_e32 v65, v2
	v_mov_b32_e32 v66, v2
	v_mov_b32_e32 v67, v2
	v_mov_b32_e32 v68, v2
	v_mov_b32_e32 v69, v2
	v_mov_b32_e32 v70, v2
	v_mov_b32_e32 v71, v2
	v_mov_b32_e32 v72, v2
	v_mov_b32_e32 v73, v2
	v_mov_b32_e32 v82, v2
	v_mov_b32_e32 v83, v2
	v_mov_b32_e32 v84, v2
	v_mov_b32_e32 v85, v2
	v_mov_b32_e32 v86, v2
	v_mov_b32_e32 v87, v2
	v_mov_b32_e32 v88, v2
	v_mov_b32_e32 v89, v2
	v_mov_b32_e32 v98, v2
	v_mov_b32_e32 v99, v2
	v_mov_b32_e32 v100, v2
	v_mov_b32_e32 v101, v2
	v_mov_b32_e32 v102, v2
	v_mov_b32_e32 v103, v2
	v_mov_b32_e32 v104, v2
	v_mov_b32_e32 v105, v2
	v_mov_b32_e32 v114, v2
	v_mov_b32_e32 v115, v2
	v_mov_b32_e32 v116, v2
	v_mov_b32_e32 v117, v2
	v_mov_b32_e32 v118, v2
	v_mov_b32_e32 v119, v2
	v_mov_b32_e32 v120, v2
	v_mov_b32_e32 v121, v2
	v_mov_b32_e32 v74, v2
	v_mov_b32_e32 v75, v2
	v_mov_b32_e32 v76, v2
	v_mov_b32_e32 v77, v2
	v_mov_b32_e32 v78, v2
	v_mov_b32_e32 v79, v2
	v_mov_b32_e32 v80, v2
	v_mov_b32_e32 v81, v2
	v_mov_b32_e32 v90, v2
	v_mov_b32_e32 v91, v2
	v_mov_b32_e32 v92, v2
	v_mov_b32_e32 v93, v2
	v_mov_b32_e32 v94, v2
	v_mov_b32_e32 v95, v2
	v_mov_b32_e32 v96, v2
	v_mov_b32_e32 v97, v2
	v_mov_b32_e32 v106, v2
	v_mov_b32_e32 v107, v2
	v_mov_b32_e32 v108, v2
	v_mov_b32_e32 v109, v2
	v_mov_b32_e32 v110, v2
	v_mov_b32_e32 v111, v2
	v_mov_b32_e32 v112, v2
	v_mov_b32_e32 v113, v2
	v_mov_b32_e32 v122, v2
	v_mov_b32_e32 v123, v2
	v_mov_b32_e32 v124, v2
	v_mov_b32_e32 v125, v2
	v_mov_b32_e32 v126, v2
	v_mov_b32_e32 v127, v2
	v_mov_b32_e32 v128, v2
	v_mov_b32_e32 v129, v2
	v_add_u32_e32 v200, 0x80, v174
	v_add_u32_e32 v218, 0x80, v158
	v_add_u32_e32 v226, 0x80, v176
	v_add_u32_e32 v228, 0x80, v160
	v_add_u32_e32 v201, 0x10000, v203
.LBB0_672:
	s_add_u32 s10, s12, 0x100
	s_addc_u32 s11, s13, 0
	s_add_i32 s23, 0, 0x10000
	ds_read_b128 v[130:133], v201
	ds_read_b128 v[134:137], v201 offset:1024
	ds_read_b128 v[138:141], v201 offset:2048
	ds_read_b128 v[142:145], v201 offset:3072
	s_cmpk_eq_i32 s22, 0x54
	s_cselect_b32 s81, s1, s11
	s_cselect_b32 s80, s0, s10
	s_cselect_b32 s63, s59, s25
	s_cselect_b32 s62, s58, s24
	s_add_i32 m0, s28, 0xc000
	ds_read_b128 v[146:149], v208
	ds_read_b128 v[150:153], v208 offset:1024
	ds_read_b128 v[154:157], v208 offset:2048
	ds_read_b128 v[162:165], v208 offset:3072
	ds_read_b128 v[170:173], v208 offset:4096
	ds_read_b128 v[184:187], v208 offset:5120
	ds_read_b128 v[188:191], v208 offset:6144
	ds_read_b128 v[192:195], v208 offset:7168
	global_load_lds_dwordx4 v182, s[12:13]
	s_add_i32 m0, s28, 0xe000
	s_nop 0
	global_load_lds_dwordx4 v180, s[12:13]
	s_waitcnt lgkmcnt(8)
	s_barrier
	s_waitcnt lgkmcnt(0)
	s_waitcnt lgkmcnt(0)
	v_mfma_f32_16x16x32_f16 v[126:129], v[130:133], v[146:149], v[126:129]
	v_mfma_f32_16x16x32_f16 v[122:125], v[138:141], v[146:149], v[122:125]
	v_mfma_f32_16x16x32_f16 v[110:113], v[130:133], v[154:157], v[110:113]
	v_mfma_f32_16x16x32_f16 v[106:109], v[138:141], v[154:157], v[106:109]
	v_mfma_f32_16x16x32_f16 v[94:97], v[130:133], v[170:173], v[94:97]
	v_mfma_f32_16x16x32_f16 v[90:93], v[138:141], v[170:173], v[90:93]
	v_mfma_f32_16x16x32_f16 v[78:81], v[130:133], v[188:191], v[78:81]
	v_mfma_f32_16x16x32_f16 v[74:77], v[138:141], v[188:191], v[74:77]
	v_mfma_f32_16x16x32_f16 v[126:129], v[134:137], v[150:153], v[126:129]
	v_mfma_f32_16x16x32_f16 v[122:125], v[142:145], v[150:153], v[122:125]
	v_mfma_f32_16x16x32_f16 v[110:113], v[134:137], v[162:165], v[110:113]
	v_mfma_f32_16x16x32_f16 v[106:109], v[142:145], v[162:165], v[106:109]
	v_mfma_f32_16x16x32_f16 v[94:97], v[134:137], v[184:187], v[94:97]
	v_mfma_f32_16x16x32_f16 v[90:93], v[142:145], v[184:187], v[90:93]
	v_mfma_f32_16x16x32_f16 v[78:81], v[134:137], v[192:195], v[78:81]
	v_mfma_f32_16x16x32_f16 v[74:77], v[142:145], v[192:195], v[74:77]
	s_barrier
	s_add_i32 s90, 0, 0x14000
	s_add_i32 s12, s23, s19
	ds_read_b128 v[196:199], v201 offset:16384
	ds_read_b128 v[210:213], v201 offset:17408
	ds_read_b128 v[214:217], v201 offset:18432
	s_mov_b32 m0, s12
	ds_read_b128 v[222:225], v201 offset:19456
	global_load_lds_dwordx4 v174, s[62:63]
	s_add_i32 m0, s12, 0x2000
	s_nop 0
	global_load_lds_dwordx4 v158, s[62:63]
	s_barrier
; #define PG8_STAGE(bufoff, gbase, voff) do { _Pragma("unroll") for (int _i = 0; _i < 2; ++_i) \
;         __builtin_amdgcn_global_load_lds((const unsigned*)((const char*)(gbase) + (voff)[_i]), (LAS unsigned*)(lds + (bufoff) + ldsw + _i * 8192), 16, 0, 0); } while (0)
; #define PG8_LDA(dst, b, h) do { _Pragma("unroll") for (int m = 0; m < 4; ++m) _Pragma("unroll") for (int k = 0; k < 2; ++k) dst[m][k] = *(const LAS f16x8*)(lds + PG8_SA(b, h) + aoff + m * 2048 + k * 1024); } while (0)
; #define PG8_LDB(dst, b, h) do { _Pragma("unroll") for (int n = 0; n < 2; ++n) _Pragma("unroll") for (int k = 0; k < 2; ++k) dst[n][k] = *(const LAS f16x8*)(lds + PG8_SB(b, h) + boff + n * 2048 + k * 1024); } while (0)
; #define PG8_MMA(ai, bj, At, Bt) do { __builtin_amdgcn_s_setprio(1); _Pragma("unroll") for (int m = 0; m < 4; ++m) _Pragma("unroll") for (int n = 0; n < 2; ++n) _Pragma("unroll") for (int k = 0; k < 2; ++k) \
;         acc[ai][bj][m][n] = __builtin_amdgcn_mfma_f32_16x16x32_f16(Bt[n][k], At[m][k], acc[ai][bj][m][n], 0, 0, 0); __builtin_amdgcn_s_setprio(0); } while (0)
; #define PG8_WAIT_V(n) asm volatile("s_waitcnt vmcnt(" #n ")" ::: "memory")
; #define PG8_WAIT_L(n) asm volatile("s_waitcnt lgkmcnt(" #n ")" ::: "memory")
; #define PG8_BAR __builtin_amdgcn_s_barrier()
; #define PG8_SCHED __builtin_amdgcn_sched_barrier(0)
; template <class Epi>
; __device__ __forceinline__ void gemm_phase(LAS unsigned char* lds, const Gemm g0, const StaticOrder& S, const Epi& E) {
;     ...
;             PG8_WAIT_L(8); PG8_BAR; PG8_WAIT_L(0); PG8_MMA(0, 0, At, B0); PG8_BAR; PG8_SCHED;
;             PG8_LDB(B1, 0, 1); PG8_STAGE(PG8_SB(0, 0), b2, voffB);
;             PG8_BAR; PG8_WAIT_L(0); PG8_MMA(0, 1, At, B1); PG8_BAR;
;             PG8_LDA(At, 0, 1); PG8_STAGE(PG8_SA(0, 0), a2, voffA);
;             PG8_BAR; PG8_WAIT_L(0); PG8_MMA(1, 0, At, B0); PG8_BAR; PG8_SCHED;
;             PG8_STAGE(PG8_SB(0, 1), b2 + hstep, voffB);
;             PG8_WAIT_V(6); PG8_BAR; PG8_MMA(1, 1, At, B1); PG8_BAR;
;             PG8_LDB(B0, 1, 0); PG8_SCHED; PG8_LDA(At, 1, 0); PG8_STAGE(PG8_SA(0, 1), a2 + hstep, voffA);
;             PG8_WAIT_L(8); PG8_BAR; PG8_WAIT_L(0); PG8_MMA(0, 0, At, B0); PG8_BAR; PG8_SCHED;
	s_waitcnt lgkmcnt(0)
	s_waitcnt lgkmcnt(0)
	v_mfma_f32_16x16x32_f16 v[118:121], v[196:199], v[146:149], v[118:121]
	v_mfma_f32_16x16x32_f16 v[114:117], v[214:217], v[146:149], v[114:117]
	v_mfma_f32_16x16x32_f16 v[102:105], v[196:199], v[154:157], v[102:105]
	v_mfma_f32_16x16x32_f16 v[98:101], v[214:217], v[154:157], v[98:101]
	v_mfma_f32_16x16x32_f16 v[86:89], v[196:199], v[170:173], v[86:89]
	v_mfma_f32_16x16x32_f16 v[82:85], v[214:217], v[170:173], v[82:85]
	v_mfma_f32_16x16x32_f16 v[70:73], v[196:199], v[188:191], v[70:73]
	v_mfma_f32_16x16x32_f16 v[66:69], v[214:217], v[188:191], v[66:69]
	v_mfma_f32_16x16x32_f16 v[118:121], v[210:213], v[150:153], v[118:121]
	v_mfma_f32_16x16x32_f16 v[114:117], v[222:225], v[150:153], v[114:117]
	v_mfma_f32_16x16x32_f16 v[102:105], v[210:213], v[162:165], v[102:105]
	v_mfma_f32_16x16x32_f16 v[98:101], v[222:225], v[162:165], v[98:101]
	v_mfma_f32_16x16x32_f16 v[86:89], v[210:213], v[184:187], v[86:89]
	v_mfma_f32_16x16x32_f16 v[82:85], v[222:225], v[184:187], v[82:85]
	v_mfma_f32_16x16x32_f16 v[70:73], v[210:213], v[192:195], v[70:73]
	v_mfma_f32_16x16x32_f16 v[66:69], v[222:225], v[192:195], v[66:69]
	s_mov_b32 m0, s28
	s_barrier
	ds_read_b128 v[146:149], v208 offset:16384
	ds_read_b128 v[150:153], v208 offset:17408
	ds_read_b128 v[154:157], v208 offset:18432
	ds_read_b128 v[162:165], v208 offset:19456
	ds_read_b128 v[170:173], v208 offset:20480
	ds_read_b128 v[184:187], v208 offset:21504
	ds_read_b128 v[188:191], v208 offset:22528
	ds_read_b128 v[192:195], v208 offset:23552
	global_load_lds_dwordx4 v176, s[80:81]
	s_mov_b32 m0, s29
	s_nop 0
	global_load_lds_dwordx4 v160, s[80:81]
	s_barrier
	s_waitcnt lgkmcnt(0)
	s_waitcnt lgkmcnt(0)
	v_mfma_f32_16x16x32_f16 v[62:65], v[130:133], v[146:149], v[62:65]
	v_mfma_f32_16x16x32_f16 v[58:61], v[138:141], v[146:149], v[58:61]
	v_mfma_f32_16x16x32_f16 v[46:49], v[130:133], v[154:157], v[46:49]
	v_mfma_f32_16x16x32_f16 v[42:45], v[138:141], v[154:157], v[42:45]
	v_mfma_f32_16x16x32_f16 v[30:33], v[130:133], v[170:173], v[30:33]
	v_mfma_f32_16x16x32_f16 v[26:29], v[138:141], v[170:173], v[26:29]
	v_mfma_f32_16x16x32_f16 v[14:17], v[130:133], v[188:191], v[14:17]
	v_mfma_f32_16x16x32_f16 v[10:13], v[138:141], v[188:191], v[10:13]
	v_mfma_f32_16x16x32_f16 v[62:65], v[134:137], v[150:153], v[62:65]
	v_mfma_f32_16x16x32_f16 v[58:61], v[142:145], v[150:153], v[58:61]
	v_mfma_f32_16x16x32_f16 v[46:49], v[134:137], v[162:165], v[46:49]
	v_mfma_f32_16x16x32_f16 v[42:45], v[142:145], v[162:165], v[42:45]
	v_mfma_f32_16x16x32_f16 v[30:33], v[134:137], v[184:187], v[30:33]
	v_mfma_f32_16x16x32_f16 v[26:29], v[142:145], v[184:187], v[26:29]
	v_mfma_f32_16x16x32_f16 v[14:17], v[134:137], v[192:195], v[14:17]
	v_mfma_f32_16x16x32_f16 v[10:13], v[142:145], v[192:195], v[10:13]
	s_barrier
	s_add_u32 s12, s62, 0x160000
	s_addc_u32 s13, s63, 0
	s_add_i32 s23, s90, s19
	s_mov_b32 m0, s23
	s_nop 0
	global_load_lds_dwordx4 v174, s[12:13]
	s_add_i32 m0, s23, 0x2000
	s_nop 0
	global_load_lds_dwordx4 v158, s[12:13]
	s_waitcnt vmcnt(6)
	s_barrier
	v_mfma_f32_16x16x32_f16 v[54:57], v[196:199], v[146:149], v[54:57]
	v_mfma_f32_16x16x32_f16 v[50:53], v[214:217], v[146:149], v[50:53]
	v_mfma_f32_16x16x32_f16 v[38:41], v[196:199], v[154:157], v[38:41]
	v_mfma_f32_16x16x32_f16 v[34:37], v[214:217], v[154:157], v[34:37]
	v_mfma_f32_16x16x32_f16 v[22:25], v[196:199], v[170:173], v[22:25]
	v_mfma_f32_16x16x32_f16 v[18:21], v[214:217], v[170:173], v[18:21]
	v_mfma_f32_16x16x32_f16 v[6:9], v[196:199], v[188:191], v[6:9]
	v_mfma_f32_16x16x32_f16 v[2:5], v[214:217], v[188:191], v[2:5]
	v_mfma_f32_16x16x32_f16 v[54:57], v[210:213], v[150:153], v[54:57]
	v_mfma_f32_16x16x32_f16 v[50:53], v[222:225], v[150:153], v[50:53]
	v_mfma_f32_16x16x32_f16 v[38:41], v[210:213], v[162:165], v[38:41]
	v_mfma_f32_16x16x32_f16 v[34:37], v[222:225], v[162:165], v[34:37]
	v_mfma_f32_16x16x32_f16 v[22:25], v[210:213], v[184:187], v[22:25]
	v_mfma_f32_16x16x32_f16 v[18:21], v[222:225], v[184:187], v[18:21]
	v_mfma_f32_16x16x32_f16 v[6:9], v[210:213], v[192:195], v[6:9]
	v_mfma_f32_16x16x32_f16 v[2:5], v[222:225], v[192:195], v[2:5]
	s_add_i32 s23, 0, 0x18000
	s_barrier
	ds_read_b128 v[130:133], v201 offset:32768
	ds_read_b128 v[134:137], v201 offset:33792
	ds_read_b128 v[138:141], v201 offset:34816
	ds_read_b128 v[142:145], v201 offset:35840
	s_add_u32 s12, s80, 0x160000
	s_addc_u32 s13, s81, 0
	s_mov_b32 m0, s31
	ds_read_b128 v[146:149], v208 offset:32768
	ds_read_b128 v[150:153], v208 offset:33792
	ds_read_b128 v[154:157], v208 offset:34816
	ds_read_b128 v[162:165], v208 offset:35840
	ds_read_b128 v[170:173], v208 offset:36864
	ds_read_b128 v[184:187], v208 offset:37888
	ds_read_b128 v[188:191], v208 offset:38912
	ds_read_b128 v[192:195], v208 offset:39936
	global_load_lds_dwordx4 v176, s[12:13]
	s_mov_b32 m0, s61
	s_nop 0
	global_load_lds_dwordx4 v160, s[12:13]
	s_waitcnt lgkmcnt(8)
	s_barrier
	s_waitcnt lgkmcnt(0)
	s_waitcnt lgkmcnt(0)
	v_mfma_f32_16x16x32_f16 v[126:129], v[130:133], v[146:149], v[126:129]
	v_mfma_f32_16x16x32_f16 v[122:125], v[138:141], v[146:149], v[122:125]
	v_mfma_f32_16x16x32_f16 v[110:113], v[130:133], v[154:157], v[110:113]
	v_mfma_f32_16x16x32_f16 v[106:109], v[138:141], v[154:157], v[106:109]
	v_mfma_f32_16x16x32_f16 v[94:97], v[130:133], v[170:173], v[94:97]
	v_mfma_f32_16x16x32_f16 v[90:93], v[138:141], v[170:173], v[90:93]
	v_mfma_f32_16x16x32_f16 v[78:81], v[130:133], v[188:191], v[78:81]
	v_mfma_f32_16x16x32_f16 v[74:77], v[138:141], v[188:191], v[74:77]
	v_mfma_f32_16x16x32_f16 v[126:129], v[134:137], v[150:153], v[126:129]
	v_mfma_f32_16x16x32_f16 v[122:125], v[142:145], v[150:153], v[122:125]
	v_mfma_f32_16x16x32_f16 v[110:113], v[134:137], v[162:165], v[110:113]
	v_mfma_f32_16x16x32_f16 v[106:109], v[142:145], v[162:165], v[106:109]
	v_mfma_f32_16x16x32_f16 v[94:97], v[134:137], v[184:187], v[94:97]
	v_mfma_f32_16x16x32_f16 v[90:93], v[142:145], v[184:187], v[90:93]
	v_mfma_f32_16x16x32_f16 v[78:81], v[134:137], v[192:195], v[78:81]
	v_mfma_f32_16x16x32_f16 v[74:77], v[142:145], v[192:195], v[74:77]
	s_barrier
; #define LAS __attribute__((address_space(3)))
; #define GAS __attribute__((address_space(1)))
;     __device__ __forceinline__ const float* resrow(int row, int colb) const { return (row < 8192 ? res0 + (size_t)row * DM : res1 + (size_t)(row - 8192) * DM) + colb; }
; #define PG8_STAGE(bufoff, gbase, voff) do { _Pragma("unroll") for (int _i = 0; _i < 2; ++_i) \
;         __builtin_amdgcn_global_load_lds((const unsigned*)((const char*)(gbase) + (voff)[_i]), (LAS unsigned*)(lds + (bufoff) + ldsw + _i * 8192), 16, 0, 0); } while (0)
; #define PG8_LDA(dst, b, h) do { _Pragma("unroll") for (int m = 0; m < 4; ++m) _Pragma("unroll") for (int k = 0; k < 2; ++k) dst[m][k] = *(const LAS f16x8*)(lds + PG8_SA(b, h) + aoff + m * 2048 + k * 1024); } while (0)
; #define PG8_WAIT_V(n) asm volatile("s_waitcnt vmcnt(" #n ")" ::: "memory")
; #define PG8_WAIT_L(n) asm volatile("s_waitcnt lgkmcnt(" #n ")" ::: "memory")
;     __device__ __forceinline__ void operator()(f32x4 (&acc)[2][2][4][2], const Unit& u, int wr, int wc, int fr, int fq) const {
;         const int row0 = u.pm * BM + wr * 64 + fr, colb = u.pn * BM + wc * 32 + 8 * fq;
;         const bool hasln = pstats != nullptr, haszh = zh != nullptr;
;         LAS float* slot = vl + (wr * 4 + wc) * 256;
;         f32x4 rn[2][2]; float ssm[8], ssq[8]; f32x2 stn = {0.f, 0.f};
;         { const int lane = fr + 16 * fq, cL = u.pn * BM + wc * 32 + (lane < 32 ? lane : 96 + lane);
;           float vg = 0.f, vb = 0.f, vt = 0.f;
;           if (hasln) { vg = *(const GAS float*)(pg + cL); vb = *(const GAS float*)(pb + cL); }
;           if (haszh) vt = *(const GAS float*)(tg + cL);
;           const float* rp = resrow(row0, colb);
; template <class Epi>
; __device__ __forceinline__ void gemm_phase(LAS unsigned char* lds, const Gemm g0, const StaticOrder& S, const Epi& E) {
;     ...
;             PG8_WAIT_L(8); PG8_BAR; PG8_WAIT_L(0); PG8_MMA(0, 0, At, B0); PG8_BAR; PG8_SCHED;
;             PG8_LDB(B1, 1, 1); PG8_STAGE(PG8_SB(1, 0), b3, voffB);
;             PG8_BAR; PG8_WAIT_L(0); PG8_MMA(0, 1, At, B1); PG8_BAR;
;             PG8_LDA(At, 1, 1); PG8_STAGE(PG8_SA(1, 0), a3, voffA);
;             PG8_BAR; PG8_WAIT_L(0); PG8_MMA(1, 0, At, B0); PG8_BAR; PG8_SCHED;
;             PG8_STAGE(PG8_SB(1, 1), b3 + hstep, voffB);
;             PG8_WAIT_V(6); PG8_BAR; PG8_MMA(1, 1, At, B1); PG8_BAR;
;         }
	s_add_i32 s90, 0, 0x1c000
	s_add_i32 s12, s23, s19
	s_mov_b32 m0, s12
	ds_read_b128 v[196:199], v201 offset:49152
	ds_read_b128 v[210:213], v201 offset:50176
	ds_read_b128 v[214:217], v201 offset:51200
	ds_read_b128 v[222:225], v201 offset:52224
	global_load_lds_dwordx4 v200, s[62:63]
	s_add_i32 m0, s12, 0x2000
	s_nop 0
	global_load_lds_dwordx4 v218, s[62:63]
	s_barrier
	s_waitcnt lgkmcnt(0)
	s_waitcnt lgkmcnt(0)
	v_mfma_f32_16x16x32_f16 v[118:121], v[196:199], v[146:149], v[118:121]
	v_mfma_f32_16x16x32_f16 v[114:117], v[214:217], v[146:149], v[114:117]
	v_mfma_f32_16x16x32_f16 v[102:105], v[196:199], v[154:157], v[102:105]
	v_mfma_f32_16x16x32_f16 v[98:101], v[214:217], v[154:157], v[98:101]
	v_mfma_f32_16x16x32_f16 v[86:89], v[196:199], v[170:173], v[86:89]
	v_mfma_f32_16x16x32_f16 v[82:85], v[214:217], v[170:173], v[82:85]
	v_mfma_f32_16x16x32_f16 v[70:73], v[196:199], v[188:191], v[70:73]
	v_mfma_f32_16x16x32_f16 v[66:69], v[214:217], v[188:191], v[66:69]
	v_mfma_f32_16x16x32_f16 v[118:121], v[210:213], v[150:153], v[118:121]
	v_mfma_f32_16x16x32_f16 v[114:117], v[222:225], v[150:153], v[114:117]
	v_mfma_f32_16x16x32_f16 v[102:105], v[210:213], v[162:165], v[102:105]
	v_mfma_f32_16x16x32_f16 v[98:101], v[222:225], v[162:165], v[98:101]
	v_mfma_f32_16x16x32_f16 v[86:89], v[210:213], v[184:187], v[86:89]
	v_mfma_f32_16x16x32_f16 v[82:85], v[222:225], v[184:187], v[82:85]
	v_mfma_f32_16x16x32_f16 v[70:73], v[210:213], v[192:195], v[70:73]
	v_mfma_f32_16x16x32_f16 v[66:69], v[222:225], v[192:195], v[66:69]
	s_mov_b32 m0, s83
	s_barrier
	ds_read_b128 v[146:149], v208 offset:49152
	ds_read_b128 v[150:153], v208 offset:50176
	ds_read_b128 v[154:157], v208 offset:51200
	ds_read_b128 v[162:165], v208 offset:52224
	ds_read_b128 v[170:173], v208 offset:53248
	ds_read_b128 v[184:187], v208 offset:54272
	ds_read_b128 v[188:191], v208 offset:55296
	ds_read_b128 v[192:195], v208 offset:56320
	global_load_lds_dwordx4 v226, s[80:81]
	s_mov_b32 m0, s84
	s_nop 0
	global_load_lds_dwordx4 v228, s[80:81]
	s_barrier
	s_waitcnt lgkmcnt(0)
	s_waitcnt lgkmcnt(0)
	v_mfma_f32_16x16x32_f16 v[62:65], v[130:133], v[146:149], v[62:65]
	v_mfma_f32_16x16x32_f16 v[58:61], v[138:141], v[146:149], v[58:61]
	v_mfma_f32_16x16x32_f16 v[46:49], v[130:133], v[154:157], v[46:49]
	v_mfma_f32_16x16x32_f16 v[42:45], v[138:141], v[154:157], v[42:45]
	v_mfma_f32_16x16x32_f16 v[30:33], v[130:133], v[170:173], v[30:33]
	v_mfma_f32_16x16x32_f16 v[26:29], v[138:141], v[170:173], v[26:29]
	v_mfma_f32_16x16x32_f16 v[14:17], v[130:133], v[188:191], v[14:17]
	v_mfma_f32_16x16x32_f16 v[10:13], v[138:141], v[188:191], v[10:13]
	v_mfma_f32_16x16x32_f16 v[62:65], v[134:137], v[150:153], v[62:65]
	v_mfma_f32_16x16x32_f16 v[58:61], v[142:145], v[150:153], v[58:61]
	v_mfma_f32_16x16x32_f16 v[46:49], v[134:137], v[162:165], v[46:49]
	v_mfma_f32_16x16x32_f16 v[42:45], v[142:145], v[162:165], v[42:45]
	v_mfma_f32_16x16x32_f16 v[30:33], v[134:137], v[184:187], v[30:33]
	v_mfma_f32_16x16x32_f16 v[26:29], v[142:145], v[184:187], v[26:29]
	v_mfma_f32_16x16x32_f16 v[14:17], v[134:137], v[192:195], v[14:17]
	v_mfma_f32_16x16x32_f16 v[10:13], v[142:145], v[192:195], v[10:13]
	s_barrier
	s_add_u32 s12, s62, 0x160080
	s_addc_u32 s13, s63, 0
	s_add_i32 s23, s90, s19
	s_mov_b32 m0, s23
	s_nop 0
	global_load_lds_dwordx4 v174, s[12:13]
	s_add_i32 m0, s23, 0x2000
	s_nop 0
	global_load_lds_dwordx4 v158, s[12:13]
	s_waitcnt vmcnt(6)
	s_barrier
	v_mfma_f32_16x16x32_f16 v[54:57], v[196:199], v[146:149], v[54:57]
	v_mfma_f32_16x16x32_f16 v[50:53], v[214:217], v[146:149], v[50:53]
	v_mfma_f32_16x16x32_f16 v[38:41], v[196:199], v[154:157], v[38:41]
	v_mfma_f32_16x16x32_f16 v[34:37], v[214:217], v[154:157], v[34:37]
	v_mfma_f32_16x16x32_f16 v[22:25], v[196:199], v[170:173], v[22:25]
	v_mfma_f32_16x16x32_f16 v[18:21], v[214:217], v[170:173], v[18:21]
	v_mfma_f32_16x16x32_f16 v[6:9], v[196:199], v[188:191], v[6:9]
	v_mfma_f32_16x16x32_f16 v[2:5], v[214:217], v[188:191], v[2:5]
	v_mfma_f32_16x16x32_f16 v[54:57], v[210:213], v[150:153], v[54:57]
	v_mfma_f32_16x16x32_f16 v[50:53], v[222:225], v[150:153], v[50:53]
	v_mfma_f32_16x16x32_f16 v[38:41], v[210:213], v[162:165], v[38:41]
	v_mfma_f32_16x16x32_f16 v[34:37], v[222:225], v[162:165], v[34:37]
	v_mfma_f32_16x16x32_f16 v[22:25], v[210:213], v[184:187], v[22:25]
	v_mfma_f32_16x16x32_f16 v[18:21], v[222:225], v[184:187], v[18:21]
	v_mfma_f32_16x16x32_f16 v[6:9], v[210:213], v[192:195], v[6:9]
	v_mfma_f32_16x16x32_f16 v[2:5], v[222:225], v[192:195], v[2:5]
	s_add_i32 s22, s22, 2
	s_add_u32 s24, s24, 0x100
	s_addc_u32 s25, s25, 0
	s_cmpk_gt_u32 s22, 0x55
	s_mov_b64 s[12:13], s[10:11]
	s_barrier
	s_cbranch_scc0 .LBB0_672
	s_lshl_b32 s10, s92, 8
	s_or_b32 s12, s10, s82
	v_add_u32_e32 v130, s12, v204
	v_ashrrev_i32_e32 v131, 31, v130
	v_lshlrev_b64 v[132:133], 2, v[130:131]
	v_lshl_add_u64 v[134:135], s[38:39], 0, v[132:133]
	v_lshl_add_u64 v[132:133], s[48:49], 0, v[132:133]
	global_load_dword v146, v[134:135], off
	global_load_dword v147, v[132:133], off
	v_readlane_b32 s22, v254, 55
	v_readlane_b32 s23, v254, 56
	s_andn2_b64 vcc, exec, s[22:23]
	v_mov_b32_e32 v148, 0
	v_cndmask_b32_e64 v132, 0, 1, s[22:23]
	v_cmp_ne_u32_e64 s[10:11], 1, v132
	s_cbranch_vccnz .LBB0_675
	v_lshl_add_u64 v[130:131], v[130:131], 2, s[50:51]
	global_load_dword v148, v[130:131], off
